# Fourier stage-1 items: 32 twiddle loads issued up front (one wait instead of 16 serialized store-ack+load waits); dilated items: K/V staging rounds 1-4 loaded together with round 0 under counted waits
# speedup vs baseline: 1.0007x; 1.0007x over previous
.LBB0_127:
	s_or_b64 exec, exec, s[14:15]
	v_or_b32_e32 v11, 1, v10
	s_waitcnt vmcnt(0)
	v_lshrrev_b32_e32 v4, 16, v4
	v_cmp_lt_u32_e32 vcc, 32, v11
	s_and_saveexec_b64 s[14:15], vcc
	s_xor_b64 s[14:15], exec, s[14:15]
	ds_write_b16 v9, v4 offset:66
	v_xor_b32_e32 v4, 0xffff8000, v4
	s_or_saveexec_b64 s[14:15], s[14:15]
	v_mov_b32_e32 v12, 0xa0
	s_xor_b64 exec, exec, s[14:15]
	v_mov_b32_e32 v12, 64
	ds_write_b16 v9, v4 offset:2
	s_or_b64 exec, exec, s[14:15]
	v_sub_u32_e32 v11, v12, v11
	v_lshl_add_u32 v11, v11, 1, v8
	ds_write_b16 v11, v4
	v_or_b32_e32 v4, 2, v10
	v_cmp_lt_u32_e32 vcc, 32, v4
	s_and_saveexec_b64 s[14:15], vcc
	s_xor_b64 s[14:15], exec, s[14:15]
	v_xor_b32_e32 v11, 0xffff8000, v5
	ds_write_b16 v9, v5 offset:68
	s_or_saveexec_b64 s[14:15], s[14:15]
	v_mov_b32_e32 v12, 0xa0
	s_xor_b64 exec, exec, s[14:15]
	v_mov_b32_e32 v12, 64
	v_mov_b32_e32 v11, v5
	ds_write_b16 v9, v5 offset:4
	s_or_b64 exec, exec, s[14:15]
	v_sub_u32_e32 v4, v12, v4
	v_lshl_add_u32 v4, v4, 1, v8
	ds_write_b16 v4, v11
	v_lshrrev_b32_e32 v4, 16, v5
	v_or_b32_e32 v5, 3, v10
	v_cmp_lt_u32_e32 vcc, 32, v5
	s_and_saveexec_b64 s[14:15], vcc
	s_xor_b64 s[14:15], exec, s[14:15]
	ds_write_b16 v9, v4 offset:70
	v_xor_b32_e32 v4, 0xffff8000, v4
	s_or_saveexec_b64 s[14:15], s[14:15]
	v_mov_b32_e32 v11, 0xa0
	s_xor_b64 exec, exec, s[14:15]
	v_mov_b32_e32 v11, 64
	ds_write_b16 v9, v4 offset:6
	s_or_b64 exec, exec, s[14:15]
	v_sub_u32_e32 v5, v11, v5
	v_lshl_add_u32 v5, v5, 1, v8
	ds_write_b16 v5, v4
	v_or_b32_e32 v4, 4, v10
	v_cmp_lt_u32_e32 vcc, 32, v4
	s_and_saveexec_b64 s[14:15], vcc
	s_xor_b64 s[14:15], exec, s[14:15]
	v_xor_b32_e32 v5, 0xffff8000, v6
	ds_write_b16 v9, v6 offset:72
	s_or_saveexec_b64 s[14:15], s[14:15]
	v_mov_b32_e32 v11, 0xa0
	s_xor_b64 exec, exec, s[14:15]
	v_mov_b32_e32 v11, 64
	v_mov_b32_e32 v5, v6
	ds_write_b16 v9, v6 offset:8
	s_or_b64 exec, exec, s[14:15]
	v_sub_u32_e32 v4, v11, v4
	v_lshl_add_u32 v4, v4, 1, v8
	ds_write_b16 v4, v5
	v_or_b32_e32 v5, 5, v10
	v_lshrrev_b32_e32 v4, 16, v6
	v_cmp_lt_u32_e32 vcc, 32, v5
	s_and_saveexec_b64 s[14:15], vcc
	s_xor_b64 s[14:15], exec, s[14:15]
	ds_write_b16 v9, v4 offset:74
	v_xor_b32_e32 v4, 0xffff8000, v4
	s_or_saveexec_b64 s[14:15], s[14:15]
	v_mov_b32_e32 v6, 0xa0
	s_xor_b64 exec, exec, s[14:15]
	v_mov_b32_e32 v6, 64
	ds_write_b16 v9, v4 offset:10
	s_or_b64 exec, exec, s[14:15]
	v_sub_u32_e32 v5, v6, v5
	v_lshl_add_u32 v5, v5, 1, v8
	ds_write_b16 v5, v4
	v_or_b32_e32 v4, 6, v10
	v_cmp_lt_u32_e32 vcc, 32, v4
	s_and_saveexec_b64 s[14:15], vcc
	s_xor_b64 s[14:15], exec, s[14:15]
	v_xor_b32_e32 v5, 0xffff8000, v7
	ds_write_b16 v9, v7 offset:76
	s_or_saveexec_b64 s[14:15], s[14:15]
	v_mov_b32_e32 v6, 0xa0
	s_xor_b64 exec, exec, s[14:15]
	v_mov_b32_e32 v6, 64
	v_mov_b32_e32 v5, v7
	ds_write_b16 v9, v7 offset:12
	s_or_b64 exec, exec, s[14:15]
	v_sub_u32_e32 v4, v6, v4
	v_lshl_add_u32 v4, v4, 1, v8
	ds_write_b16 v4, v5
	v_or_b32_e32 v5, 7, v10
	v_lshrrev_b32_e32 v4, 16, v7
	v_cmp_lt_u32_e32 vcc, 32, v5
	s_and_saveexec_b64 s[14:15], vcc
	s_xor_b64 s[14:15], exec, s[14:15]
	ds_write_b16 v9, v4 offset:78
	v_xor_b32_e32 v4, 0xffff8000, v4
	s_or_saveexec_b64 s[14:15], s[14:15]
	v_mov_b32_e32 v6, 0xa0
	s_xor_b64 exec, exec, s[14:15]
	v_mov_b32_e32 v6, 64
	ds_write_b16 v9, v4 offset:14
	s_or_b64 exec, exec, s[14:15]
	v_sub_u32_e32 v5, v6, v5
	v_lshl_add_u32 v5, v5, 1, v8
	ds_write_b16 v5, v4
	v_or_b32_e32 v4, 8, v10
	v_cmp_lt_u32_e32 vcc, 32, v4
	s_and_saveexec_b64 s[14:15], vcc
	s_xor_b64 s[14:15], exec, s[14:15]
	v_xor_b32_e32 v5, 0xffff8000, v0
	ds_write_b16 v9, v0 offset:80
	s_or_saveexec_b64 s[14:15], s[14:15]
	v_mov_b32_e32 v6, 0xa0
	s_xor_b64 exec, exec, s[14:15]
	v_mov_b32_e32 v6, 64
	v_mov_b32_e32 v5, v0
	ds_write_b16 v9, v0 offset:16
	s_or_b64 exec, exec, s[14:15]
	v_sub_u32_e32 v4, v6, v4
	v_lshl_add_u32 v4, v4, 1, v8
	ds_write_b16 v4, v5
	v_or_b32_e32 v4, 9, v10
	v_lshrrev_b32_e32 v0, 16, v0
	v_cmp_lt_u32_e32 vcc, 32, v4
	s_and_saveexec_b64 s[14:15], vcc
	s_xor_b64 s[14:15], exec, s[14:15]
	ds_write_b16 v9, v0 offset:82
	v_xor_b32_e32 v0, 0xffff8000, v0
	s_or_saveexec_b64 s[14:15], s[14:15]
	v_mov_b32_e32 v5, 0xa0
	s_xor_b64 exec, exec, s[14:15]
	v_mov_b32_e32 v5, 64
	ds_write_b16 v9, v0 offset:18
	s_or_b64 exec, exec, s[14:15]
	v_sub_u32_e32 v4, v5, v4
	v_lshl_add_u32 v4, v4, 1, v8
	ds_write_b16 v4, v0
	v_or_b32_e32 v0, 10, v10
	v_cmp_lt_u32_e32 vcc, 32, v0
	s_and_saveexec_b64 s[14:15], vcc
	s_xor_b64 s[14:15], exec, s[14:15]
	v_xor_b32_e32 v4, 0xffff8000, v1
	ds_write_b16 v9, v1 offset:84
	s_or_saveexec_b64 s[14:15], s[14:15]
	v_mov_b32_e32 v5, 0xa0
	s_xor_b64 exec, exec, s[14:15]
	v_mov_b32_e32 v5, 64
	v_mov_b32_e32 v4, v1
	ds_write_b16 v9, v1 offset:20
	s_or_b64 exec, exec, s[14:15]
	v_sub_u32_e32 v0, v5, v0
	v_lshl_add_u32 v0, v0, 1, v8
	ds_write_b16 v0, v4
	v_lshrrev_b32_e32 v0, 16, v1
	v_or_b32_e32 v1, 11, v10
	v_cmp_lt_u32_e32 vcc, 32, v1
	s_and_saveexec_b64 s[14:15], vcc
	s_xor_b64 s[14:15], exec, s[14:15]
	ds_write_b16 v9, v0 offset:86
	v_xor_b32_e32 v0, 0xffff8000, v0
	s_or_saveexec_b64 s[14:15], s[14:15]
	v_mov_b32_e32 v4, 0xa0
	s_xor_b64 exec, exec, s[14:15]
	v_mov_b32_e32 v4, 64
	ds_write_b16 v9, v0 offset:22
	s_or_b64 exec, exec, s[14:15]
	v_sub_u32_e32 v1, v4, v1
	v_lshl_add_u32 v1, v1, 1, v8
	ds_write_b16 v1, v0
	v_or_b32_e32 v0, 12, v10
	v_cmp_lt_u32_e32 vcc, 32, v0
	s_and_saveexec_b64 s[14:15], vcc
	s_xor_b64 s[14:15], exec, s[14:15]
	v_xor_b32_e32 v1, 0xffff8000, v2
	ds_write_b16 v9, v2 offset:88
	s_or_saveexec_b64 s[14:15], s[14:15]
	v_mov_b32_e32 v4, 0xa0
	s_xor_b64 exec, exec, s[14:15]
	v_mov_b32_e32 v4, 64
	v_mov_b32_e32 v1, v2
	ds_write_b16 v9, v2 offset:24
	s_or_b64 exec, exec, s[14:15]
	v_sub_u32_e32 v0, v4, v0
	v_lshl_add_u32 v0, v0, 1, v8
	ds_write_b16 v0, v1
	v_or_b32_e32 v1, 13, v10
	v_lshrrev_b32_e32 v0, 16, v2
	v_cmp_lt_u32_e32 vcc, 32, v1
	s_and_saveexec_b64 s[14:15], vcc
	s_xor_b64 s[14:15], exec, s[14:15]
	ds_write_b16 v9, v0 offset:90
	v_xor_b32_e32 v0, 0xffff8000, v0
	s_or_saveexec_b64 s[14:15], s[14:15]
	v_mov_b32_e32 v2, 0xa0
	s_xor_b64 exec, exec, s[14:15]
	v_mov_b32_e32 v2, 64
	ds_write_b16 v9, v0 offset:26
	s_or_b64 exec, exec, s[14:15]
	v_sub_u32_e32 v1, v2, v1
	v_lshl_add_u32 v1, v1, 1, v8
	ds_write_b16 v1, v0
	v_or_b32_e32 v0, 14, v10
	v_cmp_lt_u32_e32 vcc, 32, v0
	s_and_saveexec_b64 s[14:15], vcc
	s_xor_b64 s[14:15], exec, s[14:15]
	v_xor_b32_e32 v1, 0xffff8000, v3
	ds_write_b16 v9, v3 offset:92
	s_or_saveexec_b64 s[14:15], s[14:15]
	v_mov_b32_e32 v2, 0xa0
	s_xor_b64 exec, exec, s[14:15]
	v_mov_b32_e32 v2, 64
	v_mov_b32_e32 v1, v3
	ds_write_b16 v9, v3 offset:28
	s_or_b64 exec, exec, s[14:15]
	v_sub_u32_e32 v0, v2, v0
	v_lshl_add_u32 v0, v0, 1, v8
	ds_write_b16 v0, v1
	v_or_b32_e32 v1, 15, v10
	v_lshrrev_b32_e32 v0, 16, v3
	v_cmp_lt_u32_e32 vcc, 32, v1
	s_and_saveexec_b64 s[14:15], vcc
	s_xor_b64 s[14:15], exec, s[14:15]
	ds_write_b16 v9, v0 offset:94
	v_xor_b32_e32 v0, 0xffff8000, v0
	s_or_saveexec_b64 s[14:15], s[14:15]
	v_mov_b32_e32 v2, 0xa0
	s_xor_b64 exec, exec, s[14:15]
	v_mov_b32_e32 v2, 64
	ds_write_b16 v9, v0 offset:30
	s_or_b64 exec, exec, s[14:15]
	v_sub_u32_e32 v1, v2, v1
	v_lshl_add_u32 v1, v1, 1, v8
	ds_write_b16 v1, v0
	v_lshlrev_b32_e32 v0, 5, v194
	v_and_b32_e32 v45, 0x60, v0
	v_or_b32_e32 v0, v45, v195
	v_readlane_b32 s14, v255, 36
	v_lshlrev_b32_e32 v168, 8, v0
	v_readlane_b32 s15, v255, 37
	v_lshlrev_b32_e32 v2, 4, v193
	v_mov_b32_e32 v3, v169
	v_lshl_add_u64 v[0:1], s[14:15], 0, v[168:169]
	v_lshl_add_u64 v[32:33], v[0:1], 0, v[2:3]
	v_lshl_add_u64 v[0:1], s[48:49], 0, v[168:169]
	s_waitcnt lgkmcnt(0)
	s_barrier
	v_lshl_add_u64 v[34:35], v[0:1], 0, v[2:3]
	global_load_dwordx4 v[16:19], v[32:33], off
	global_load_dwordx4 v[40:43], v[34:35], off
	v_ashrrev_i32_e32 v0, 3, v97
	v_lshlrev_b32_e32 v2, 2, v98
	v_and_b32_e32 v44, 0xffffffe0, v0
	v_and_b32_e32 v1, 16, v97
	v_and_b32_e32 v2, 12, v2
	v_bfe_u32 v0, v97, 2, 2
	v_or3_b32 v3, v2, v1, v44
	v_lshlrev_b32_e32 v3, 1, v3
	v_lshl_or_b32 v0, v193, 3, v0
	v_or3_b32 v1, v44, v1, v2
	v_mul_u32_u24_e32 v2, 0x140, v0
	v_mad_u32_u24 v38, v0, s60, v3
	v_lshl_add_u32 v46, v1, 1, v2
	ds_read_b64_tr_b16 v[48:49], v38
	ds_read_b64_tr_b16 v[50:51], v38 offset:1280
	ds_read_b64_tr_b16 v[20:21], v46 offset:128
	ds_read_b64_tr_b16 v[22:23], v46 offset:1408
	s_mov_b32 s5, 0x8000
	s_mov_b32 s14, 0x5040100
	s_waitcnt lgkmcnt(2)
	v_xor_b32_e32 v36, 0x8000, v51
	v_xor_b32_sdwa v37, s5, v51 dst_sel:DWORD dst_unused:UNUSED_PAD src0_sel:DWORD src1_sel:WORD_1
	v_readlane_b32 s16, v254, 62
	v_readlane_b32 s17, v254, 63
	s_waitcnt vmcnt(1)
	v_mfma_f32_32x32x16_bf16 v[0:15], v[16:19], v[48:51], 0
	v_perm_b32 v51, v37, v36, s14
	v_xor_b32_e32 v36, 0x8000, v50
	v_xor_b32_sdwa v37, s5, v50 dst_sel:DWORD dst_unused:UNUSED_PAD src0_sel:DWORD src1_sel:WORD_1
	v_perm_b32 v50, v37, v36, s14
	v_xor_b32_e32 v36, 0x8000, v49
	v_xor_b32_sdwa v37, s5, v49 dst_sel:DWORD dst_unused:UNUSED_PAD src0_sel:DWORD src1_sel:WORD_1
	v_perm_b32 v49, v37, v36, s14
	s_waitcnt vmcnt(0) lgkmcnt(0)
	v_mfma_f32_32x32x16_bf16 v[0:15], v[40:43], v[20:23], v[0:15]
	v_xor_b32_e32 v36, 0x8000, v48
	v_xor_b32_sdwa v37, s5, v48 dst_sel:DWORD dst_unused:UNUSED_PAD src0_sel:DWORD src1_sel:WORD_1
	v_perm_b32 v48, v37, v36, s14
	v_mfma_f32_32x32x16_bf16 v[16:31], v[16:19], v[20:23], 0
	s_nop 0
	v_mfma_f32_32x32x16_bf16 v[16:31], v[40:43], v[48:51], v[16:31]
	global_load_dwordx4 v[40:43], v[32:33], off offset:32
	global_load_dwordx4 v[48:51], v[34:35], off offset:32
	ds_read_b64_tr_b16 v[52:53], v38 offset:5120
	ds_read_b64_tr_b16 v[54:55], v38 offset:6400
	ds_read_b64_tr_b16 v[56:57], v46 offset:5248
	ds_read_b64_tr_b16 v[58:59], v46 offset:6528
	s_waitcnt lgkmcnt(2)
	v_xor_b32_e32 v36, 0x8000, v55
	v_xor_b32_sdwa v37, s5, v55 dst_sel:DWORD dst_unused:UNUSED_PAD src0_sel:DWORD src1_sel:WORD_1
	s_waitcnt vmcnt(1)
	v_mfma_f32_32x32x16_bf16 v[0:15], v[40:43], v[52:55], v[0:15]
	s_waitcnt lgkmcnt(0)
	v_mfma_f32_32x32x16_bf16 v[16:31], v[40:43], v[56:59], v[16:31]
	v_perm_b32 v43, v37, v36, s14
	v_xor_b32_e32 v36, 0x8000, v54
	v_xor_b32_sdwa v37, s5, v54 dst_sel:DWORD dst_unused:UNUSED_PAD src0_sel:DWORD src1_sel:WORD_1
	v_perm_b32 v42, v37, v36, s14
	v_xor_b32_e32 v36, 0x8000, v53
	v_xor_b32_sdwa v37, s5, v53 dst_sel:DWORD dst_unused:UNUSED_PAD src0_sel:DWORD src1_sel:WORD_1
	v_perm_b32 v41, v37, v36, s14
	v_xor_b32_e32 v36, 0x8000, v52
	v_xor_b32_sdwa v37, s5, v52 dst_sel:DWORD dst_unused:UNUSED_PAD src0_sel:DWORD src1_sel:WORD_1
	v_perm_b32 v40, v37, v36, s14
	s_waitcnt vmcnt(0)
	v_mfma_f32_32x32x16_bf16 v[0:15], v[48:51], v[56:59], v[0:15]
	v_mfma_f32_32x32x16_bf16 v[16:31], v[48:51], v[40:43], v[16:31]
	global_load_dwordx4 v[40:43], v[32:33], off offset:64
	global_load_dwordx4 v[48:51], v[34:35], off offset:64
	ds_read_b64_tr_b16 v[52:53], v38 offset:10240
	ds_read_b64_tr_b16 v[54:55], v38 offset:11520
	ds_read_b64_tr_b16 v[56:57], v46 offset:10368
	ds_read_b64_tr_b16 v[58:59], v46 offset:11648
	s_waitcnt lgkmcnt(2)
	v_xor_b32_e32 v36, 0x8000, v55
	v_xor_b32_sdwa v37, s5, v55 dst_sel:DWORD dst_unused:UNUSED_PAD src0_sel:DWORD src1_sel:WORD_1
	s_waitcnt vmcnt(1)
	v_mfma_f32_32x32x16_bf16 v[0:15], v[40:43], v[52:55], v[0:15]
	s_waitcnt lgkmcnt(0)
	v_mfma_f32_32x32x16_bf16 v[16:31], v[40:43], v[56:59], v[16:31]
	v_perm_b32 v43, v37, v36, s14
	v_xor_b32_e32 v36, 0x8000, v54
	v_xor_b32_sdwa v37, s5, v54 dst_sel:DWORD dst_unused:UNUSED_PAD src0_sel:DWORD src1_sel:WORD_1
	v_perm_b32 v42, v37, v36, s14
	v_xor_b32_e32 v36, 0x8000, v53
	v_xor_b32_sdwa v37, s5, v53 dst_sel:DWORD dst_unused:UNUSED_PAD src0_sel:DWORD src1_sel:WORD_1
	v_perm_b32 v41, v37, v36, s14
	v_xor_b32_e32 v36, 0x8000, v52
	v_xor_b32_sdwa v37, s5, v52 dst_sel:DWORD dst_unused:UNUSED_PAD src0_sel:DWORD src1_sel:WORD_1
	v_perm_b32 v40, v37, v36, s14
	s_waitcnt vmcnt(0)
	v_mfma_f32_32x32x16_bf16 v[0:15], v[48:51], v[56:59], v[0:15]
	v_mfma_f32_32x32x16_bf16 v[16:31], v[48:51], v[40:43], v[16:31]
	global_load_dwordx4 v[40:43], v[32:33], off offset:96
	global_load_dwordx4 v[48:51], v[34:35], off offset:96
	ds_read_b64_tr_b16 v[52:53], v38 offset:15360
	ds_read_b64_tr_b16 v[54:55], v38 offset:16640
	ds_read_b64_tr_b16 v[56:57], v46 offset:15488
	ds_read_b64_tr_b16 v[58:59], v46 offset:16768
	s_waitcnt lgkmcnt(2)
	v_xor_b32_e32 v36, 0x8000, v55
	v_xor_b32_sdwa v37, s5, v55 dst_sel:DWORD dst_unused:UNUSED_PAD src0_sel:DWORD src1_sel:WORD_1
	s_waitcnt vmcnt(1)
	v_mfma_f32_32x32x16_bf16 v[0:15], v[40:43], v[52:55], v[0:15]
	s_waitcnt lgkmcnt(0)
	v_mfma_f32_32x32x16_bf16 v[16:31], v[40:43], v[56:59], v[16:31]
	v_perm_b32 v43, v37, v36, s14
	v_xor_b32_e32 v36, 0x8000, v54
	v_xor_b32_sdwa v37, s5, v54 dst_sel:DWORD dst_unused:UNUSED_PAD src0_sel:DWORD src1_sel:WORD_1
	v_perm_b32 v42, v37, v36, s14
	v_xor_b32_e32 v36, 0x8000, v53
	v_xor_b32_sdwa v37, s5, v53 dst_sel:DWORD dst_unused:UNUSED_PAD src0_sel:DWORD src1_sel:WORD_1
	v_perm_b32 v41, v37, v36, s14
	v_xor_b32_e32 v36, 0x8000, v52
	v_xor_b32_sdwa v37, s5, v52 dst_sel:DWORD dst_unused:UNUSED_PAD src0_sel:DWORD src1_sel:WORD_1
	v_perm_b32 v40, v37, v36, s14
	s_waitcnt vmcnt(0)
	v_mfma_f32_32x32x16_bf16 v[0:15], v[48:51], v[56:59], v[0:15]
	v_mfma_f32_32x32x16_bf16 v[16:31], v[48:51], v[40:43], v[16:31]
	global_load_dwordx4 v[40:43], v[32:33], off offset:128
	global_load_dwordx4 v[48:51], v[34:35], off offset:128
	ds_read_b64_tr_b16 v[52:53], v38 offset:20480
	ds_read_b64_tr_b16 v[54:55], v38 offset:21760
	ds_read_b64_tr_b16 v[56:57], v46 offset:20608
	ds_read_b64_tr_b16 v[58:59], v46 offset:21888
	s_waitcnt lgkmcnt(2)
	v_xor_b32_e32 v36, 0x8000, v55
	v_xor_b32_sdwa v37, s5, v55 dst_sel:DWORD dst_unused:UNUSED_PAD src0_sel:DWORD src1_sel:WORD_1
	s_waitcnt vmcnt(1)
	v_mfma_f32_32x32x16_bf16 v[0:15], v[40:43], v[52:55], v[0:15]
	s_waitcnt lgkmcnt(0)
	v_mfma_f32_32x32x16_bf16 v[16:31], v[40:43], v[56:59], v[16:31]
	v_perm_b32 v43, v37, v36, s14
	v_xor_b32_e32 v36, 0x8000, v54
	v_xor_b32_sdwa v37, s5, v54 dst_sel:DWORD dst_unused:UNUSED_PAD src0_sel:DWORD src1_sel:WORD_1
	v_perm_b32 v42, v37, v36, s14
	v_xor_b32_e32 v36, 0x8000, v53
	v_xor_b32_sdwa v37, s5, v53 dst_sel:DWORD dst_unused:UNUSED_PAD src0_sel:DWORD src1_sel:WORD_1
	v_perm_b32 v41, v37, v36, s14
	v_xor_b32_e32 v36, 0x8000, v52
	v_xor_b32_sdwa v37, s5, v52 dst_sel:DWORD dst_unused:UNUSED_PAD src0_sel:DWORD src1_sel:WORD_1
	v_perm_b32 v40, v37, v36, s14
	s_waitcnt vmcnt(0)
	v_mfma_f32_32x32x16_bf16 v[0:15], v[48:51], v[56:59], v[0:15]
	v_mfma_f32_32x32x16_bf16 v[16:31], v[48:51], v[40:43], v[16:31]
	global_load_dwordx4 v[40:43], v[32:33], off offset:160
	global_load_dwordx4 v[48:51], v[34:35], off offset:160
	ds_read_b64_tr_b16 v[52:53], v38 offset:25600
	ds_read_b64_tr_b16 v[54:55], v38 offset:26880
	ds_read_b64_tr_b16 v[56:57], v46 offset:25728
	ds_read_b64_tr_b16 v[58:59], v46 offset:27008
	s_waitcnt lgkmcnt(2)
	v_xor_b32_e32 v36, 0x8000, v55
	v_xor_b32_sdwa v37, s5, v55 dst_sel:DWORD dst_unused:UNUSED_PAD src0_sel:DWORD src1_sel:WORD_1
	s_waitcnt vmcnt(1)
	v_mfma_f32_32x32x16_bf16 v[0:15], v[40:43], v[52:55], v[0:15]
	s_waitcnt lgkmcnt(0)
	v_mfma_f32_32x32x16_bf16 v[16:31], v[40:43], v[56:59], v[16:31]
	v_perm_b32 v43, v37, v36, s14
	v_xor_b32_e32 v36, 0x8000, v54
	v_xor_b32_sdwa v37, s5, v54 dst_sel:DWORD dst_unused:UNUSED_PAD src0_sel:DWORD src1_sel:WORD_1
	v_perm_b32 v42, v37, v36, s14
	v_xor_b32_e32 v36, 0x8000, v53
	v_xor_b32_sdwa v37, s5, v53 dst_sel:DWORD dst_unused:UNUSED_PAD src0_sel:DWORD src1_sel:WORD_1
	v_perm_b32 v41, v37, v36, s14
	v_xor_b32_e32 v36, 0x8000, v52
	v_xor_b32_sdwa v37, s5, v52 dst_sel:DWORD dst_unused:UNUSED_PAD src0_sel:DWORD src1_sel:WORD_1
	v_perm_b32 v40, v37, v36, s14
	s_waitcnt vmcnt(0)
	v_mfma_f32_32x32x16_bf16 v[0:15], v[48:51], v[56:59], v[0:15]
	v_mfma_f32_32x32x16_bf16 v[16:31], v[48:51], v[40:43], v[16:31]
	global_load_dwordx4 v[40:43], v[32:33], off offset:192
	global_load_dwordx4 v[48:51], v[34:35], off offset:192
	ds_read_b64_tr_b16 v[52:53], v38 offset:30720
	ds_read_b64_tr_b16 v[54:55], v38 offset:32000
	ds_read_b64_tr_b16 v[56:57], v46 offset:30848
	ds_read_b64_tr_b16 v[58:59], v46 offset:32128
	s_waitcnt lgkmcnt(2)
	v_xor_b32_e32 v36, 0x8000, v55
	v_xor_b32_sdwa v37, s5, v55 dst_sel:DWORD dst_unused:UNUSED_PAD src0_sel:DWORD src1_sel:WORD_1
	s_waitcnt vmcnt(1) lgkmcnt(0)
	v_mfma_f32_32x32x16_bf16 v[16:31], v[40:43], v[56:59], v[16:31]
	v_mfma_f32_32x32x16_bf16 v[0:15], v[40:43], v[52:55], v[0:15]
	v_perm_b32 v43, v37, v36, s14
	v_xor_b32_e32 v36, 0x8000, v54
	v_xor_b32_sdwa v37, s5, v54 dst_sel:DWORD dst_unused:UNUSED_PAD src0_sel:DWORD src1_sel:WORD_1
	v_perm_b32 v42, v37, v36, s14
	v_xor_b32_e32 v36, 0x8000, v53
	v_xor_b32_sdwa v37, s5, v53 dst_sel:DWORD dst_unused:UNUSED_PAD src0_sel:DWORD src1_sel:WORD_1
	v_perm_b32 v41, v37, v36, s14
	v_xor_b32_e32 v36, 0x8000, v52
	v_xor_b32_sdwa v37, s5, v52 dst_sel:DWORD dst_unused:UNUSED_PAD src0_sel:DWORD src1_sel:WORD_1
	v_perm_b32 v40, v37, v36, s14
	s_waitcnt vmcnt(0)
	v_mfma_f32_32x32x16_bf16 v[0:15], v[48:51], v[56:59], v[0:15]
	v_mfma_f32_32x32x16_bf16 v[16:31], v[48:51], v[40:43], v[16:31]
	global_load_dwordx4 v[40:43], v[32:33], off offset:224
	s_nop 0
	global_load_dwordx4 v[32:35], v[34:35], off offset:224
	ds_read_b64_tr_b16 v[36:37], v38 offset:35840
	ds_read_b64_tr_b16 v[38:39], v38 offset:37120
	ds_read_b64_tr_b16 v[48:49], v46 offset:35968
	ds_read_b64_tr_b16 v[50:51], v46 offset:37248
	s_waitcnt vmcnt(1) lgkmcnt(0)
	v_mfma_f32_32x32x16_bf16 v[16:31], v[40:43], v[48:51], v[16:31]
	v_mfma_f32_32x32x16_bf16 v[0:15], v[40:43], v[36:39], v[0:15]
	v_xor_b32_e32 v40, 0x8000, v39
	v_xor_b32_sdwa v39, s5, v39 dst_sel:DWORD dst_unused:UNUSED_PAD src0_sel:DWORD src1_sel:WORD_1
	v_perm_b32 v39, v39, v40, s14
	v_xor_b32_e32 v40, 0x8000, v38
	v_xor_b32_sdwa v38, s5, v38 dst_sel:DWORD dst_unused:UNUSED_PAD src0_sel:DWORD src1_sel:WORD_1
	v_perm_b32 v38, v38, v40, s14
	v_xor_b32_e32 v40, 0x8000, v37
	v_xor_b32_sdwa v37, s5, v37 dst_sel:DWORD dst_unused:UNUSED_PAD src0_sel:DWORD src1_sel:WORD_1
	v_perm_b32 v37, v37, v40, s14
	v_xor_b32_e32 v40, 0x8000, v36
	v_xor_b32_sdwa v36, s5, v36 dst_sel:DWORD dst_unused:UNUSED_PAD src0_sel:DWORD src1_sel:WORD_1
	v_perm_b32 v36, v36, v40, s14
	s_and_b64 s[14:15], s[42:43], exec
	s_movk_i32 s5, 0xfff
	s_waitcnt vmcnt(0)
	v_mfma_f32_32x32x16_bf16 v[16:31], v[32:35], v[36:39], v[16:31]
	v_lshl_or_b32 v36, v193, 2, v45
	s_cselect_b32 s5, s5, 0x1fff
	v_cndmask_b32_e64 v37, 0, 1, s[42:43]
	s_lshl_b32 s14, s56, 8
	s_add_u32 s42, s16, s14
	s_addc_u32 s43, s17, 0
	s_mul_i32 s14, s55, 5
	v_mfma_f32_32x32x16_bf16 v[0:15], v[32:35], v[48:51], v[0:15]
	v_mul_u32_u24_e32 v32, s55, v36
	v_and_b32_e32 v32, s5, v32
	v_lshlrev_b32_e32 v32, v37, v32
	v_lshlrev_b32_e32 v32, 2, v32
	v_add_u32_e32 v240, 0, v36
	v_mul_u32_u24_e32 v240, s55, v240
	v_and_b32_e32 v240, s5, v240
	v_lshlrev_b32_e32 v240, v37, v240
	v_lshlrev_b32_e32 v240, 2, v240
	global_load_dword v208, v240, s[44:45]
	global_load_dword v224, v240, s[94:95]
	v_add_u32_e32 v240, 1, v36
	v_mul_u32_u24_e32 v240, s55, v240
	v_and_b32_e32 v240, s5, v240
	v_lshlrev_b32_e32 v240, v37, v240
	v_lshlrev_b32_e32 v240, 2, v240
	global_load_dword v209, v240, s[44:45]
	global_load_dword v225, v240, s[94:95]
	v_add_u32_e32 v240, 2, v36
	v_mul_u32_u24_e32 v240, s55, v240
	v_and_b32_e32 v240, s5, v240
	v_lshlrev_b32_e32 v240, v37, v240
	v_lshlrev_b32_e32 v240, 2, v240
	global_load_dword v210, v240, s[44:45]
	global_load_dword v226, v240, s[94:95]
	v_add_u32_e32 v240, 3, v36
	v_mul_u32_u24_e32 v240, s55, v240
	v_and_b32_e32 v240, s5, v240
	v_lshlrev_b32_e32 v240, v37, v240
	v_lshlrev_b32_e32 v240, 2, v240
	global_load_dword v211, v240, s[44:45]
	global_load_dword v227, v240, s[94:95]
	v_add_u32_e32 v240, 8, v36
	v_mul_u32_u24_e32 v240, s55, v240
	v_and_b32_e32 v240, s5, v240
	v_lshlrev_b32_e32 v240, v37, v240
	v_lshlrev_b32_e32 v240, 2, v240
	global_load_dword v212, v240, s[44:45]
	global_load_dword v228, v240, s[94:95]
	v_add_u32_e32 v240, 9, v36
	v_mul_u32_u24_e32 v240, s55, v240
	v_and_b32_e32 v240, s5, v240
	v_lshlrev_b32_e32 v240, v37, v240
	v_lshlrev_b32_e32 v240, 2, v240
	global_load_dword v213, v240, s[44:45]
	global_load_dword v229, v240, s[94:95]
	v_add_u32_e32 v240, 10, v36
	v_mul_u32_u24_e32 v240, s55, v240
	v_and_b32_e32 v240, s5, v240
	v_lshlrev_b32_e32 v240, v37, v240
	v_lshlrev_b32_e32 v240, 2, v240
	global_load_dword v214, v240, s[44:45]
	global_load_dword v230, v240, s[94:95]
	v_add_u32_e32 v240, 11, v36
	v_mul_u32_u24_e32 v240, s55, v240
	v_and_b32_e32 v240, s5, v240
	v_lshlrev_b32_e32 v240, v37, v240
	v_lshlrev_b32_e32 v240, 2, v240
	global_load_dword v215, v240, s[44:45]
	global_load_dword v231, v240, s[94:95]
	v_add_u32_e32 v240, 16, v36
	v_mul_u32_u24_e32 v240, s55, v240
	v_and_b32_e32 v240, s5, v240
	v_lshlrev_b32_e32 v240, v37, v240
	v_lshlrev_b32_e32 v240, 2, v240
	global_load_dword v216, v240, s[44:45]
	global_load_dword v232, v240, s[94:95]
	v_add_u32_e32 v240, 17, v36
	v_mul_u32_u24_e32 v240, s55, v240
	v_and_b32_e32 v240, s5, v240
	v_lshlrev_b32_e32 v240, v37, v240
	v_lshlrev_b32_e32 v240, 2, v240
	global_load_dword v217, v240, s[44:45]
	global_load_dword v233, v240, s[94:95]
	v_add_u32_e32 v240, 18, v36
	v_mul_u32_u24_e32 v240, s55, v240
	v_and_b32_e32 v240, s5, v240
	v_lshlrev_b32_e32 v240, v37, v240
	v_lshlrev_b32_e32 v240, 2, v240
	global_load_dword v218, v240, s[44:45]
	global_load_dword v234, v240, s[94:95]
	v_add_u32_e32 v240, 19, v36
	v_mul_u32_u24_e32 v240, s55, v240
	v_and_b32_e32 v240, s5, v240
	v_lshlrev_b32_e32 v240, v37, v240
	v_lshlrev_b32_e32 v240, 2, v240
	global_load_dword v219, v240, s[44:45]
	global_load_dword v235, v240, s[94:95]
	v_add_u32_e32 v240, 24, v36
	v_mul_u32_u24_e32 v240, s55, v240
	v_and_b32_e32 v240, s5, v240
	v_lshlrev_b32_e32 v240, v37, v240
	v_lshlrev_b32_e32 v240, 2, v240
	global_load_dword v220, v240, s[44:45]
	global_load_dword v236, v240, s[94:95]
	v_add_u32_e32 v240, 25, v36
	v_mul_u32_u24_e32 v240, s55, v240
	v_and_b32_e32 v240, s5, v240
	v_lshlrev_b32_e32 v240, v37, v240
	v_lshlrev_b32_e32 v240, 2, v240
	global_load_dword v221, v240, s[44:45]
	global_load_dword v237, v240, s[94:95]
	v_add_u32_e32 v240, 26, v36
	v_mul_u32_u24_e32 v240, s55, v240
	v_and_b32_e32 v240, s5, v240
	v_lshlrev_b32_e32 v240, v37, v240
	v_lshlrev_b32_e32 v240, 2, v240
	global_load_dword v222, v240, s[44:45]
	global_load_dword v238, v240, s[94:95]
	v_add_u32_e32 v240, 27, v36
	v_mul_u32_u24_e32 v240, s55, v240
	v_and_b32_e32 v240, s5, v240
	v_lshlrev_b32_e32 v240, v37, v240
	v_lshlrev_b32_e32 v240, 2, v240
	global_load_dword v223, v240, s[44:45]
	global_load_dword v239, v240, s[94:95]
	v_lshlrev_b32_e32 v32, s26, v36
	v_add_u32_e32 v32, s27, v32
	v_ashrrev_i32_e32 v33, 31, v32
	v_lshlrev_b64 v[32:33], 10, v[32:33]
	v_or_b32_e32 v34, v44, v195
	v_lshl_add_u64 v[38:39], s[42:43], 0, v[32:33]
	v_ashrrev_i32_e32 v35, 31, v34
	s_waitcnt vmcnt(0)
	v_mul_f32_e32 v32, v16, v224
	v_fmac_f32_e32 v32, v0, v208
	v_mul_f32_e32 v0, v0, v224
	v_fma_f32 v0, v16, v208, -v0
	v_cvt_pk_bf16_f32 v16, v32, s0
	v_lshlrev_b64 v[32:33], 1, v[34:35]
	v_ashrrev_i32_e32 v35, 31, v44
	v_lshl_add_u64 v[40:41], v[38:39], 0, v[32:33]
	v_lshlrev_b64 v[34:35], 1, v[34:35]
	global_store_short v[40:41], v16, off
	v_cvt_pk_bf16_f32 v0, v0, s0
	v_lshl_add_u64 v[38:39], v[38:39], 0, v[34:35]
	v_mad_u32_u24 v16, v36, s55, s55
	global_store_short v[38:39], v0, off offset:128
	v_and_b32_e32 v38, s5, v16
	v_lshlrev_b32_e32 v38, v37, v38
	v_lshlrev_b32_e32 v38, 2, v38
	v_or_b32_e32 v0, 1, v36
	v_lshlrev_b32_e32 v0, s26, v0
	v_add_u32_e32 v38, s27, v0
	v_ashrrev_i32_e32 v39, 31, v38
	v_lshlrev_b64 v[38:39], 10, v[38:39]
	v_lshl_add_u64 v[38:39], s[42:43], 0, v[38:39]
	v_mul_f32_e32 v0, v17, v225
	v_fmac_f32_e32 v0, v1, v209
	v_mul_f32_e32 v1, v1, v225
	v_fma_f32 v17, v17, v209, -v1
	v_cvt_pk_bf16_f32 v40, v0, s0
	v_lshl_add_u64 v[0:1], v[38:39], 0, v[32:33]
	global_store_short v[0:1], v40, off
	v_cvt_pk_bf16_f32 v17, v17, s0
	v_lshl_add_u64 v[0:1], v[38:39], 0, v[34:35]
	v_add_u32_e32 v38, s55, v16
	global_store_short v[0:1], v17, off offset:128
	v_and_b32_e32 v1, s5, v38
	v_lshlrev_b32_e32 v1, v37, v1
	v_lshlrev_b32_e32 v1, 2, v1
	v_or_b32_e32 v0, 2, v36
	v_lshlrev_b32_e32 v0, s26, v0
	v_add_u32_e32 v0, s27, v0
	v_ashrrev_i32_e32 v1, 31, v0
	v_lshlrev_b64 v[0:1], 10, v[0:1]
	v_lshl_add_u64 v[0:1], s[42:43], 0, v[0:1]
	v_mul_f32_e32 v39, v18, v226
	v_fmac_f32_e32 v39, v2, v210
	v_mul_f32_e32 v2, v2, v226
	v_fma_f32 v2, v18, v210, -v2
	v_cvt_pk_bf16_f32 v18, v39, s0
	v_lshl_add_u64 v[16:17], v[0:1], 0, v[32:33]
	global_store_short v[16:17], v18, off
	v_cvt_pk_bf16_f32 v2, v2, s0
	v_lshl_add_u64 v[0:1], v[0:1], 0, v[34:35]
	v_add_u32_e32 v16, s55, v38
	global_store_short v[0:1], v2, off offset:128
	v_and_b32_e32 v1, s5, v16
	v_lshlrev_b32_e32 v1, v37, v1
	v_lshlrev_b32_e32 v1, 2, v1
	v_or_b32_e32 v0, 3, v36
	v_lshlrev_b32_e32 v0, s26, v0
	v_add_u32_e32 v0, s27, v0
	v_ashrrev_i32_e32 v1, 31, v0
	v_lshlrev_b64 v[0:1], 10, v[0:1]
	v_lshl_add_u64 v[0:1], s[42:43], 0, v[0:1]
	v_add_u32_e32 v16, s14, v16
	v_mul_f32_e32 v18, v19, v227
	v_fmac_f32_e32 v18, v3, v211
	v_mul_f32_e32 v3, v3, v227
	v_fma_f32 v17, v19, v211, -v3
	v_cvt_pk_bf16_f32 v18, v18, s0
	v_lshl_add_u64 v[2:3], v[0:1], 0, v[32:33]
	global_store_short v[2:3], v18, off
	v_cvt_pk_bf16_f32 v2, v17, s0
	v_lshl_add_u64 v[0:1], v[0:1], 0, v[34:35]
	global_store_short v[0:1], v2, off offset:128
	v_and_b32_e32 v1, s5, v16
	v_lshlrev_b32_e32 v1, v37, v1
	v_lshlrev_b32_e32 v1, 2, v1
	v_or_b32_e32 v0, 8, v36
	v_lshlrev_b32_e32 v0, s26, v0
	v_add_u32_e32 v0, s27, v0
	v_ashrrev_i32_e32 v1, 31, v0
	v_lshlrev_b64 v[0:1], 10, v[0:1]
	v_lshl_add_u64 v[0:1], s[42:43], 0, v[0:1]
	v_mul_f32_e32 v17, v20, v228
	v_fmac_f32_e32 v17, v4, v212
	v_mul_f32_e32 v3, v4, v228
	v_fma_f32 v4, v20, v212, -v3
	v_cvt_pk_bf16_f32 v17, v17, s0
	v_lshl_add_u64 v[2:3], v[0:1], 0, v[32:33]
	global_store_short v[2:3], v17, off
	v_cvt_pk_bf16_f32 v2, v4, s0
	v_lshl_add_u64 v[0:1], v[0:1], 0, v[34:35]
	v_add_u32_e32 v4, s55, v16
	global_store_short v[0:1], v2, off offset:128
	v_and_b32_e32 v1, s5, v4
	v_lshlrev_b32_e32 v1, v37, v1
	v_lshlrev_b32_e32 v1, 2, v1
	v_or_b32_e32 v0, 9, v36
	v_lshlrev_b32_e32 v0, s26, v0
	v_add_u32_e32 v0, s27, v0
	v_ashrrev_i32_e32 v1, 31, v0
	v_lshlrev_b64 v[0:1], 10, v[0:1]
	v_lshl_add_u64 v[0:1], s[42:43], 0, v[0:1]
	v_add_u32_e32 v4, s55, v4
	v_mul_f32_e32 v16, v21, v229
	v_fmac_f32_e32 v16, v5, v213
	v_mul_f32_e32 v3, v5, v229
	v_fma_f32 v5, v21, v213, -v3
	v_cvt_pk_bf16_f32 v16, v16, s0
	v_lshl_add_u64 v[2:3], v[0:1], 0, v[32:33]
	global_store_short v[2:3], v16, off
	v_cvt_pk_bf16_f32 v2, v5, s0
	v_lshl_add_u64 v[0:1], v[0:1], 0, v[34:35]
	global_store_short v[0:1], v2, off offset:128
	v_and_b32_e32 v1, s5, v4
	v_lshlrev_b32_e32 v1, v37, v1
	v_lshlrev_b32_e32 v1, 2, v1
	v_or_b32_e32 v0, 10, v36
	v_lshlrev_b32_e32 v0, s26, v0
	v_add_u32_e32 v0, s27, v0
	v_ashrrev_i32_e32 v1, 31, v0
	v_lshlrev_b64 v[0:1], 10, v[0:1]
	v_lshl_add_u64 v[0:1], s[42:43], 0, v[0:1]
	v_add_u32_e32 v4, s55, v4
	v_mul_f32_e32 v5, v22, v230
	v_fmac_f32_e32 v5, v6, v214
	v_mul_f32_e32 v3, v6, v230
	v_fma_f32 v6, v22, v214, -v3
	v_cvt_pk_bf16_f32 v5, v5, s0
	v_lshl_add_u64 v[2:3], v[0:1], 0, v[32:33]
	global_store_short v[2:3], v5, off
	v_cvt_pk_bf16_f32 v2, v6, s0
	v_lshl_add_u64 v[0:1], v[0:1], 0, v[34:35]
	global_store_short v[0:1], v2, off offset:128
	v_and_b32_e32 v1, s5, v4
	v_lshlrev_b32_e32 v1, v37, v1
	v_lshlrev_b32_e32 v1, 2, v1
	v_or_b32_e32 v0, 11, v36
	v_lshlrev_b32_e32 v0, s26, v0
	v_add_u32_e32 v0, s27, v0
	v_ashrrev_i32_e32 v1, 31, v0
	v_lshlrev_b64 v[0:1], 10, v[0:1]
	v_lshl_add_u64 v[0:1], s[42:43], 0, v[0:1]
	v_add_u32_e32 v4, s14, v4
	v_mul_f32_e32 v5, v23, v231
	v_fmac_f32_e32 v5, v7, v215
	v_mul_f32_e32 v3, v7, v231
	v_fma_f32 v6, v23, v215, -v3
	v_cvt_pk_bf16_f32 v5, v5, s0
	v_lshl_add_u64 v[2:3], v[0:1], 0, v[32:33]
	global_store_short v[2:3], v5, off
	v_cvt_pk_bf16_f32 v2, v6, s0
	v_lshl_add_u64 v[0:1], v[0:1], 0, v[34:35]
	global_store_short v[0:1], v2, off offset:128
	v_and_b32_e32 v1, s5, v4
	v_lshlrev_b32_e32 v1, v37, v1
	v_lshlrev_b32_e32 v1, 2, v1
	v_or_b32_e32 v0, 16, v36
	v_lshlrev_b32_e32 v0, s26, v0
	v_add_u32_e32 v0, s27, v0
	v_ashrrev_i32_e32 v1, 31, v0
	v_lshlrev_b64 v[0:1], 10, v[0:1]
	v_lshl_add_u64 v[0:1], s[42:43], 0, v[0:1]
	v_add_u32_e32 v4, s55, v4
	v_mul_f32_e32 v5, v24, v232
	v_fmac_f32_e32 v5, v8, v216
	v_mul_f32_e32 v3, v8, v232
	v_fma_f32 v6, v24, v216, -v3
	v_cvt_pk_bf16_f32 v5, v5, s0
	v_lshl_add_u64 v[2:3], v[0:1], 0, v[32:33]
	global_store_short v[2:3], v5, off
	v_cvt_pk_bf16_f32 v2, v6, s0
	v_lshl_add_u64 v[0:1], v[0:1], 0, v[34:35]
	global_store_short v[0:1], v2, off offset:128
	v_and_b32_e32 v1, s5, v4
	v_lshlrev_b32_e32 v1, v37, v1
	v_lshlrev_b32_e32 v1, 2, v1
	v_or_b32_e32 v0, 17, v36
	v_lshlrev_b32_e32 v0, s26, v0
	v_add_u32_e32 v0, s27, v0
	v_ashrrev_i32_e32 v1, 31, v0
	v_lshlrev_b64 v[0:1], 10, v[0:1]
	v_lshl_add_u64 v[0:1], s[42:43], 0, v[0:1]
	v_add_u32_e32 v4, s55, v4
	v_mul_f32_e32 v5, v25, v233
	v_fmac_f32_e32 v5, v9, v217
	v_mul_f32_e32 v3, v9, v233
	v_fma_f32 v6, v25, v217, -v3
	v_cvt_pk_bf16_f32 v5, v5, s0
	v_lshl_add_u64 v[2:3], v[0:1], 0, v[32:33]
	global_store_short v[2:3], v5, off
	v_cvt_pk_bf16_f32 v2, v6, s0
	v_lshl_add_u64 v[0:1], v[0:1], 0, v[34:35]
	global_store_short v[0:1], v2, off offset:128
	v_and_b32_e32 v1, s5, v4
	v_lshlrev_b32_e32 v1, v37, v1
	v_lshlrev_b32_e32 v1, 2, v1
	v_or_b32_e32 v0, 18, v36
	v_lshlrev_b32_e32 v0, s26, v0
	v_add_u32_e32 v0, s27, v0
	v_ashrrev_i32_e32 v1, 31, v0
	v_lshlrev_b64 v[0:1], 10, v[0:1]
	v_lshl_add_u64 v[0:1], s[42:43], 0, v[0:1]
	v_add_u32_e32 v4, s55, v4
	v_mul_f32_e32 v5, v26, v234
	v_fmac_f32_e32 v5, v10, v218
	v_mul_f32_e32 v3, v10, v234
	v_fma_f32 v6, v26, v218, -v3
	v_cvt_pk_bf16_f32 v5, v5, s0
	v_lshl_add_u64 v[2:3], v[0:1], 0, v[32:33]
	global_store_short v[2:3], v5, off
	v_cvt_pk_bf16_f32 v2, v6, s0
	v_lshl_add_u64 v[0:1], v[0:1], 0, v[34:35]
	global_store_short v[0:1], v2, off offset:128
	v_and_b32_e32 v1, s5, v4
	v_lshlrev_b32_e32 v1, v37, v1
	v_lshlrev_b32_e32 v1, 2, v1
	v_or_b32_e32 v0, 19, v36
	v_lshlrev_b32_e32 v0, s26, v0
	v_add_u32_e32 v0, s27, v0
	v_ashrrev_i32_e32 v1, 31, v0
	v_lshlrev_b64 v[0:1], 10, v[0:1]
	v_lshl_add_u64 v[0:1], s[42:43], 0, v[0:1]
	v_add_u32_e32 v4, s14, v4
	s_mov_b64 s[14:15], 0
	v_mul_f32_e32 v5, v27, v235
	v_fmac_f32_e32 v5, v11, v219
	v_mul_f32_e32 v3, v11, v235
	v_fma_f32 v6, v27, v219, -v3
	v_cvt_pk_bf16_f32 v5, v5, s0
	v_lshl_add_u64 v[2:3], v[0:1], 0, v[32:33]
	global_store_short v[2:3], v5, off
	v_cvt_pk_bf16_f32 v2, v6, s0
	v_lshl_add_u64 v[0:1], v[0:1], 0, v[34:35]
	global_store_short v[0:1], v2, off offset:128
	v_and_b32_e32 v1, s5, v4
	v_lshlrev_b32_e32 v1, v37, v1
	v_lshlrev_b32_e32 v1, 2, v1
	v_or_b32_e32 v0, 24, v36
	v_lshlrev_b32_e32 v0, s26, v0
	v_add_u32_e32 v0, s27, v0
	v_ashrrev_i32_e32 v1, 31, v0
	v_lshlrev_b64 v[0:1], 10, v[0:1]
	v_lshl_add_u64 v[0:1], s[42:43], 0, v[0:1]
	v_add_u32_e32 v4, s55, v4
	v_mul_f32_e32 v5, v28, v236
	v_fmac_f32_e32 v5, v12, v220
	v_mul_f32_e32 v3, v12, v236
	v_fma_f32 v6, v28, v220, -v3
	v_cvt_pk_bf16_f32 v5, v5, s0
	v_lshl_add_u64 v[2:3], v[0:1], 0, v[32:33]
	global_store_short v[2:3], v5, off
	v_cvt_pk_bf16_f32 v2, v6, s0
	v_lshl_add_u64 v[0:1], v[0:1], 0, v[34:35]
	global_store_short v[0:1], v2, off offset:128
	v_and_b32_e32 v1, s5, v4
	v_lshlrev_b32_e32 v1, v37, v1
	v_lshlrev_b32_e32 v1, 2, v1
	v_or_b32_e32 v0, 25, v36
	v_lshlrev_b32_e32 v0, s26, v0
	v_add_u32_e32 v0, s27, v0
	v_ashrrev_i32_e32 v1, 31, v0
	v_lshlrev_b64 v[0:1], 10, v[0:1]
	v_lshl_add_u64 v[0:1], s[42:43], 0, v[0:1]
	v_add_u32_e32 v4, s55, v4
	v_mul_f32_e32 v5, v29, v237
	v_fmac_f32_e32 v5, v13, v221
	v_mul_f32_e32 v3, v13, v237
	v_fma_f32 v6, v29, v221, -v3
	v_cvt_pk_bf16_f32 v5, v5, s0
	v_lshl_add_u64 v[2:3], v[0:1], 0, v[32:33]
	global_store_short v[2:3], v5, off
	v_cvt_pk_bf16_f32 v2, v6, s0
	v_lshl_add_u64 v[0:1], v[0:1], 0, v[34:35]
	global_store_short v[0:1], v2, off offset:128
	v_and_b32_e32 v1, s5, v4
	v_lshlrev_b32_e32 v1, v37, v1
	v_lshlrev_b32_e32 v1, 2, v1
	v_or_b32_e32 v0, 26, v36
	v_lshlrev_b32_e32 v0, s26, v0
	v_add_u32_e32 v0, s27, v0
	v_ashrrev_i32_e32 v1, 31, v0
	v_lshlrev_b64 v[0:1], 10, v[0:1]
	v_lshl_add_u64 v[0:1], s[42:43], 0, v[0:1]
	v_mul_f32_e32 v5, v30, v238
	v_fmac_f32_e32 v5, v14, v222
	v_mul_f32_e32 v3, v14, v238
	v_fma_f32 v6, v30, v222, -v3
	v_cvt_pk_bf16_f32 v5, v5, s0
	v_lshl_add_u64 v[2:3], v[0:1], 0, v[32:33]
	global_store_short v[2:3], v5, off
	v_cvt_pk_bf16_f32 v2, v6, s0
	v_lshl_add_u64 v[0:1], v[0:1], 0, v[34:35]
	global_store_short v[0:1], v2, off offset:128
	v_add_u32_e32 v1, s55, v4
	v_and_b32_e32 v1, s5, v1
	v_lshlrev_b32_e32 v1, v37, v1
	v_lshlrev_b32_e32 v1, 2, v1
	v_or_b32_e32 v0, 27, v36
	v_lshlrev_b32_e32 v0, s26, v0
	v_add_u32_e32 v0, s27, v0
	v_ashrrev_i32_e32 v1, 31, v0
	v_lshlrev_b64 v[0:1], 10, v[0:1]
	v_lshl_add_u64 v[0:1], s[42:43], 0, v[0:1]
	v_mul_f32_e32 v4, v31, v239
	v_fmac_f32_e32 v4, v15, v223
	v_mul_f32_e32 v3, v15, v239
	v_fma_f32 v5, v31, v223, -v3
	v_cvt_pk_bf16_f32 v4, v4, s0
	v_lshl_add_u64 v[2:3], v[0:1], 0, v[32:33]
	global_store_short v[2:3], v4, off
	v_cvt_pk_bf16_f32 v2, v5, s0
	v_lshl_add_u64 v[0:1], v[0:1], 0, v[34:35]
	global_store_short v[0:1], v2, off offset:128
	s_barrier
.LBB0_188:
	s_and_b64 vcc, exec, s[14:15]
	s_cbranch_vccz .LBB0_192
	s_add_i32 s15, s54, 0xfffff600
	s_and_b32 s5, s15, 0xffff
	s_mul_i32 s5, s5, 0xcccd
	s_lshr_b32 s14, s5, 26
	s_mul_i32 s5, s14, 0x500
	s_sub_i32 s16, s15, s5
	s_bfe_u32 s18, s16, 0xe0002
	s_add_i32 s19, s18, 0xffffff00
	s_lshr_b32 s19, s19, 4
	s_and_b32 s17, s16, 0xffff
	s_and_b32 s5, s16, 3
	s_add_i32 s19, s19, 8
	s_bfe_u32 s16, s16, 0x90007
	s_cmpk_lt_u32 s17, 0x400
	s_cselect_b32 s17, 31, 15
	s_cselect_b32 s16, s16, s19
	s_and_b32 s17, s18, s17
	s_lshl_b32 s18, s16, 12
	s_add_i32 s18, s18, 0x8000
	s_lshl_b32 s19, s16, 13
	s_add_i32 s24, s54, 0xfffff100
	s_cmp_lt_u32 s16, 8
	s_movk_i32 s16, 0x1000
	s_cselect_b32 s19, s19, s18
	s_cselect_b32 s16, 0x2000, s16
	s_cselect_b32 s26, 13, 12
	s_cmpk_lt_u32 s24, 0x500
	s_cselect_b32 s18, 2, 4
	s_cmpk_gt_u32 s15, 0x4ff
	s_cselect_b32 s15, s18, 0
	s_lshr_b32 s18, s16, s15
	s_lshl_b32 s16, s17, 8
	s_sub_i32 s17, s26, s15
	s_add_i32 s24, s18, -1
	s_lshr_b32 s17, s16, s17
	s_and_b32 s16, s24, s16
	s_lshl_b32 s30, s5, 7
	v_readlane_b32 s26, v255, 32
	v_readlane_b32 s27, v255, 33
	s_add_u32 s26, s26, s30
	s_addc_u32 s27, s27, 0
	v_readlane_b32 s28, v255, 20
	v_readlane_b32 s29, v255, 21
	s_add_u32 s28, s28, s30
	s_addc_u32 s29, s29, 0
	v_readlane_b32 s36, v255, 16
	v_readlane_b32 s37, v255, 17
	s_add_u32 s36, s36, s30
	s_waitcnt vmcnt(5)
	v_bfe_u32 v4, v97, 2, 1
	s_addc_u32 s37, s37, 0
	s_or_b32 s17, s19, s17
	s_sub_i32 s19, s16, 64
	v_mul_u32_u24_e32 v4, 0x6000, v4
	v_lshlrev_b32_e32 v5, 4, v97
	s_waitcnt vmcnt(1)
	v_ashrrev_i32_e32 v13, 3, v97
	v_and_or_b32 v12, v5, 48, v4
	v_add_u32_e32 v4, s19, v13
	v_min_i32_e32 v5, s24, v4
	v_cmp_lt_i32_e32 vcc, -1, v4
	v_and_b32_e32 v0, 7, v97
	v_lshlrev_b32_e32 v168, 4, v0
	v_cndmask_b32_e32 v4, 0, v5, vcc
	v_lshlrev_b32_e32 v4, s15, v4
	v_add_u32_e32 v4, s17, v4
	v_ashrrev_i32_e32 v5, 31, v4
	v_lshl_add_u64 v[2:3], s[28:29], 0, v[168:169]
	v_lshlrev_b64 v[8:9], 9, v[4:5]
	v_lshl_add_u64 v[0:1], s[36:37], 0, v[168:169]
	v_lshl_add_u64 v[4:5], v[2:3], 0, v[8:9]
	global_load_dwordx4 v[4:7], v[4:5], off
	v_lshl_add_u64 v[8:9], v[0:1], 0, v[8:9]
	global_load_dwordx4 v[8:11], v[8:9], off
	v_add_u32_e32 v200, 0x200, v97
	v_ashrrev_i32_e32 v208, 3, v200
	v_add_u32_e32 v200, s19, v208
	v_min_i32_e32 v201, s24, v200
	v_cmp_lt_i32_e32 vcc, -1, v200
	v_lshrrev_b32_e32 v210, 1, v208
	v_xor_b32_e32 v210, v210, v97
	v_cndmask_b32_e32 v200, 0, v201, vcc
	v_lshlrev_b32_e32 v200, s15, v200
	v_add_u32_e32 v200, s17, v200
	v_ashrrev_i32_e32 v201, 31, v200
	v_lshlrev_b64 v[204:205], 9, v[200:201]
	v_lshl_add_u64 v[200:201], v[2:3], 0, v[204:205]
	global_load_dwordx4 v[200:203], v[200:201], off
	v_lshl_add_u64 v[204:205], v[0:1], 0, v[204:205]
	global_load_dwordx4 v[204:207], v[204:205], off
	v_add_u32_e32 v212, 0x400, v97
	v_ashrrev_i32_e32 v220, 3, v212
	v_add_u32_e32 v212, s19, v220
	v_min_i32_e32 v213, s24, v212
	v_cmp_lt_i32_e32 vcc, -1, v212
	v_lshrrev_b32_e32 v222, 1, v220
	v_xor_b32_e32 v222, v222, v97
	v_cndmask_b32_e32 v212, 0, v213, vcc
	v_lshlrev_b32_e32 v212, s15, v212
	v_add_u32_e32 v212, s17, v212
	v_ashrrev_i32_e32 v213, 31, v212
	v_lshlrev_b64 v[216:217], 9, v[212:213]
	v_lshl_add_u64 v[212:213], v[2:3], 0, v[216:217]
	global_load_dwordx4 v[212:215], v[212:213], off
	v_lshl_add_u64 v[216:217], v[0:1], 0, v[216:217]
	global_load_dwordx4 v[216:219], v[216:217], off
	v_add_u32_e32 v224, 0x600, v97
	v_ashrrev_i32_e32 v232, 3, v224
	v_add_u32_e32 v224, s19, v232
	v_min_i32_e32 v225, s24, v224
	v_cmp_lt_i32_e32 vcc, -1, v224
	v_lshrrev_b32_e32 v234, 1, v232
	v_xor_b32_e32 v234, v234, v97
	v_cndmask_b32_e32 v224, 0, v225, vcc
	v_lshlrev_b32_e32 v224, s15, v224
	v_add_u32_e32 v224, s17, v224
	v_ashrrev_i32_e32 v225, 31, v224
	v_lshlrev_b64 v[228:229], 9, v[224:225]
	v_lshl_add_u64 v[224:225], v[2:3], 0, v[228:229]
	global_load_dwordx4 v[224:227], v[224:225], off
	v_lshl_add_u64 v[228:229], v[0:1], 0, v[228:229]
	global_load_dwordx4 v[228:231], v[228:229], off
	v_add_u32_e32 v236, 0x800, v97
	v_ashrrev_i32_e32 v244, 3, v236
	v_add_u32_e32 v236, s19, v244
	v_min_i32_e32 v237, s24, v236
	v_cmp_lt_i32_e32 vcc, -1, v236
	v_lshrrev_b32_e32 v246, 1, v244
	v_xor_b32_e32 v246, v246, v97
	v_cndmask_b32_e32 v236, 0, v237, vcc
	v_lshlrev_b32_e32 v236, s15, v236
	v_add_u32_e32 v236, s17, v236
	v_ashrrev_i32_e32 v237, 31, v236
	v_lshlrev_b64 v[240:241], 9, v[236:237]
	v_lshl_add_u64 v[236:237], v[2:3], 0, v[240:241]
	global_load_dwordx4 v[236:239], v[236:237], off
	v_lshl_add_u64 v[240:241], v[0:1], 0, v[240:241]
	global_load_dwordx4 v[240:243], v[240:241], off
	v_lshrrev_b32_e32 v15, 1, v13
	v_xor_b32_e32 v15, v15, v97
	v_lshlrev_b32_e32 v14, 7, v13
	v_lshlrev_b32_e32 v15, 4, v15
	s_movk_i32 s28, 0x70
	v_and_or_b32 v14, v15, s28, v14
	v_bfe_u32 v20, v97, 1, 3
	v_bitop3_b32 v16, v193, v20, 2 bitop3:0x36
	v_lshlrev_b32_e32 v107, 4, v16
	v_lshlrev_b32_e32 v21, 2, v193
	v_or_b32_e32 v103, s19, v21
	v_lshrrev_b32_e32 v22, 2, v97
	v_and_or_b32 v104, v22, 3, v21
	s_mul_i32 s14, s14, 0x14000
	v_lshlrev_b32_e32 v168, 3, v193
	s_waitcnt vmcnt(9)
	ds_write_b128 v14, v[4:7]
	v_lshl_add_u32 v4, v13, 6, v12
	s_waitcnt vmcnt(8)
	ds_write_b128 v4, v[8:11] offset:49152
	v_lshlrev_b32_e32 v209, 7, v208
	v_lshlrev_b32_e32 v210, 4, v210
	v_and_or_b32 v209, v210, s28, v209
	s_waitcnt vmcnt(7)
	ds_write_b128 v209, v[200:203]
	v_lshl_add_u32 v200, v208, 6, v12
	s_waitcnt vmcnt(6)
	ds_write_b128 v200, v[204:207] offset:49152
	v_lshlrev_b32_e32 v221, 7, v220
	v_lshlrev_b32_e32 v222, 4, v222
	v_and_or_b32 v221, v222, s28, v221
	s_waitcnt vmcnt(5)
	ds_write_b128 v221, v[212:215]
	v_lshl_add_u32 v212, v220, 6, v12
	s_waitcnt vmcnt(4)
	ds_write_b128 v212, v[216:219] offset:49152
	v_lshlrev_b32_e32 v233, 7, v232
	v_lshlrev_b32_e32 v234, 4, v234
	v_and_or_b32 v233, v234, s28, v233
	s_waitcnt vmcnt(3)
	ds_write_b128 v233, v[224:227]
	v_lshl_add_u32 v224, v232, 6, v12
	s_waitcnt vmcnt(2)
	ds_write_b128 v224, v[228:231] offset:49152
	v_lshlrev_b32_e32 v245, 7, v244
	v_lshlrev_b32_e32 v246, 4, v246
	v_and_or_b32 v245, v246, s28, v245
	s_waitcnt vmcnt(1)
	ds_write_b128 v245, v[236:239]
	v_lshl_add_u32 v236, v244, 6, v12
	s_waitcnt vmcnt(0)
	ds_write_b128 v236, v[240:243] offset:49152
	v_add_u32_e32 v4, 0xa00, v97
	v_ashrrev_i32_e32 v10, 3, v4
	v_add_u32_e32 v4, s19, v10
	v_min_i32_e32 v5, s24, v4
	v_cmp_lt_i32_e32 vcc, -1, v4
	s_mov_b32 s19, 0xf149f2ca
	s_movk_i32 s24, 0x200
	v_cndmask_b32_e32 v4, 0, v5, vcc
	v_lshlrev_b32_e32 v4, s15, v4
	v_add_u32_e32 v4, s17, v4
	v_ashrrev_i32_e32 v5, 31, v4
	v_lshlrev_b64 v[6:7], 9, v[4:5]
	v_lshl_add_u64 v[2:3], v[2:3], 0, v[6:7]
	global_load_dwordx4 v[2:5], v[2:3], off
	v_lshl_add_u64 v[0:1], v[0:1], 0, v[6:7]
	global_load_dwordx4 v[6:9], v[0:1], off
	v_lshrrev_b32_e32 v1, 1, v10
	v_xor_b32_e32 v1, v1, v97
	v_lshlrev_b32_e32 v0, 7, v10
	v_lshlrev_b32_e32 v1, 4, v1
	v_and_or_b32 v0, v1, s28, v0
	s_waitcnt vmcnt(1)
	ds_write_b128 v0, v[2:5]
	v_lshl_add_u32 v0, v10, 6, v12
	s_waitcnt vmcnt(0)
	ds_write_b128 v0, v[6:9] offset:49152
	v_ashrrev_i32_e32 v0, 1, v97
	v_and_b32_e32 v102, 0xffffffe0, v0
	v_or_b32_e32 v4, v102, v195
	v_add_u32_e32 v101, s16, v4
	v_lshlrev_b32_e32 v0, s15, v101
	v_add_u32_e32 v0, s17, v0
	v_ashrrev_i32_e32 v1, 31, v0
	v_lshlrev_b64 v[0:1], 9, v[0:1]
	v_lshl_add_u64 v[0:1], s[26:27], 0, v[0:1]
	v_lshlrev_b32_e32 v2, 4, v193
	v_mov_b32_e32 v3, v169
	v_lshl_add_u64 v[0:1], v[0:1], 0, v[2:3]
	global_load_dwordx4 v[60:63], v[0:1], off
	global_load_dwordx4 v[52:55], v[0:1], off offset:32
	global_load_dwordx4 v[56:59], v[0:1], off offset:64
	global_load_dwordx4 v[48:51], v[0:1], off offset:96
	v_and_b32_e32 v2, 64, v182
	v_xor_b32_e32 v1, 32, v182
	v_add_u32_e32 v2, 64, v2
	v_lshrrev_b32_e32 v0, 1, v97
	v_cmp_lt_i32_e32 vcc, v1, v2
	v_bitop3_b32 v0, v193, v0, 7 bitop3:0x78
	v_lshlrev_b32_e32 v2, 2, v98
	v_cndmask_b32_e32 v1, v182, v1, vcc
	v_lshlrev_b32_e32 v99, 2, v1
	v_and_b32_e32 v1, 16, v97
	v_lshlrev_b32_e32 v23, 7, v4
	v_lshlrev_b32_e32 v108, 4, v0
	v_and_or_b32 v1, v2, 12, v1
	v_or_b32_e32 v0, v23, v108
	s_waitcnt lgkmcnt(0)
	s_barrier
	v_lshlrev_b32_e32 v100, 1, v1
	ds_read_b128 v[0:3], v0
	v_or_b32_e32 v16, v23, v107
	ds_read_b128 v[16:19], v16
	s_waitcnt vmcnt(3) lgkmcnt(1)
	v_mfma_f32_32x32x16_bf16 v[0:15], v[0:3], v[60:63], 0
	s_movk_i32 s27, 0x81
	s_movk_i32 s26, 0x600
	v_add_u32_e32 v73, 32, v102
	v_add_u32_e32 v114, 64, v102
	s_waitcnt vmcnt(2) lgkmcnt(0)
	v_mfma_f32_32x32x16_bf16 v[0:15], v[16:19], v[52:55], v[0:15]
	v_bitop3_b32 v16, v193, v20, 4 bitop3:0x36
	v_lshlrev_b32_e32 v106, 4, v16
	v_or_b32_e32 v16, v23, v106
	ds_read_b128 v[16:19], v16
	s_waitcnt vmcnt(1) lgkmcnt(0)
	v_mfma_f32_32x32x16_bf16 v[0:15], v[16:19], v[56:59], v[0:15]
	v_bitop3_b32 v16, v193, v20, 6 bitop3:0x36
	v_lshlrev_b32_e32 v105, 4, v16
	v_or_b32_e32 v16, v23, v105
	ds_read_b128 v[16:19], v16
	s_waitcnt vmcnt(0) lgkmcnt(0)
	v_mfma_f32_32x32x16_bf16 v[0:15], v[16:19], v[48:51], v[0:15]
	v_add_u32_e32 v16, v103, v102
	v_sub_u32_e32 v17, v16, v101
	v_add_u32_e32 v18, 64, v17
	v_cmp_gt_u32_e32 vcc, s27, v18
	v_cmp_gt_u32_e64 s[42:43], s18, v16
	s_and_b64 vcc, s[42:43], vcc
	v_or_b32_e32 v18, 1, v16
	v_add_u32_e32 v19, 0x41, v17
	s_nop 3
	v_cndmask_b32_e32 v0, v183, v0, vcc
	v_cmp_gt_u32_e32 vcc, s27, v19
	v_cmp_gt_u32_e64 s[42:43], s18, v18
	s_and_b64 vcc, s[42:43], vcc
	v_or_b32_e32 v18, 2, v16
	v_add_u32_e32 v19, 0x42, v17
	v_cndmask_b32_e32 v1, v183, v1, vcc
	v_cmp_gt_u32_e32 vcc, s27, v19
	v_cmp_gt_u32_e64 s[42:43], s18, v18
	s_and_b64 vcc, s[42:43], vcc
	v_or_b32_e32 v18, 3, v16
	v_add_u32_e32 v19, 0x43, v17
	v_cndmask_b32_e32 v2, v183, v2, vcc
	v_cmp_gt_u32_e32 vcc, s27, v19
	v_cmp_gt_u32_e64 s[42:43], s18, v18
	s_and_b64 vcc, s[42:43], vcc
	v_or_b32_e32 v18, 8, v16
	v_add_u32_e32 v19, 0x48, v17
	v_cndmask_b32_e32 v3, v183, v3, vcc
	v_cmp_gt_u32_e32 vcc, s27, v19
	v_cmp_gt_u32_e64 s[42:43], s18, v18
	s_and_b64 vcc, s[42:43], vcc
	v_or_b32_e32 v18, 9, v16
	v_add_u32_e32 v19, 0x49, v17
	v_cndmask_b32_e32 v4, v183, v4, vcc
	v_cmp_gt_u32_e32 vcc, s27, v19
	v_cmp_gt_u32_e64 s[42:43], s18, v18
	s_and_b64 vcc, s[42:43], vcc
	v_or_b32_e32 v18, 10, v16
	v_add_u32_e32 v19, 0x4a, v17
	v_cndmask_b32_e32 v5, v183, v5, vcc
	v_cmp_gt_u32_e32 vcc, s27, v19
	v_cmp_gt_u32_e64 s[42:43], s18, v18
	s_and_b64 vcc, s[42:43], vcc
	v_or_b32_e32 v18, 11, v16
	v_add_u32_e32 v19, 0x4b, v17
	v_cndmask_b32_e32 v6, v183, v6, vcc
	v_cmp_gt_u32_e32 vcc, s27, v19
	v_cmp_gt_u32_e64 s[42:43], s18, v18
	s_and_b64 vcc, s[42:43], vcc
	v_or_b32_e32 v18, 16, v16
	v_add_u32_e32 v19, 0x50, v17
	v_cndmask_b32_e32 v7, v183, v7, vcc
	v_cmp_gt_u32_e32 vcc, s27, v19
	v_cmp_gt_u32_e64 s[42:43], s18, v18
	s_and_b64 vcc, s[42:43], vcc
	v_or_b32_e32 v18, 17, v16
	v_add_u32_e32 v19, 0x51, v17
	v_cndmask_b32_e32 v8, v183, v8, vcc
	v_cmp_gt_u32_e32 vcc, s27, v19
	v_cmp_gt_u32_e64 s[42:43], s18, v18
	s_and_b64 vcc, s[42:43], vcc
	v_or_b32_e32 v18, 18, v16
	v_add_u32_e32 v19, 0x52, v17
	v_cndmask_b32_e32 v9, v183, v9, vcc
	v_cmp_gt_u32_e32 vcc, s27, v19
	v_cmp_gt_u32_e64 s[42:43], s18, v18
	s_and_b64 vcc, s[42:43], vcc
	v_or_b32_e32 v18, 19, v16
	v_add_u32_e32 v19, 0x53, v17
	v_cndmask_b32_e32 v10, v183, v10, vcc
	v_cmp_gt_u32_e32 vcc, s27, v19
	v_cmp_gt_u32_e64 s[42:43], s18, v18
	s_and_b64 vcc, s[42:43], vcc
	v_or_b32_e32 v18, 24, v16
	v_add_u32_e32 v19, 0x58, v17
	v_cndmask_b32_e32 v11, v183, v11, vcc
	v_cmp_gt_u32_e32 vcc, s27, v19
	v_cmp_gt_u32_e64 s[42:43], s18, v18
	s_and_b64 vcc, s[42:43], vcc
	v_or_b32_e32 v18, 25, v16
	v_add_u32_e32 v19, 0x59, v17
	v_cndmask_b32_e32 v12, v183, v12, vcc
	v_cmp_gt_u32_e32 vcc, s27, v19
	v_cmp_gt_u32_e64 s[42:43], s18, v18
	s_and_b64 vcc, s[42:43], vcc
	v_or_b32_e32 v18, 26, v16
	v_add_u32_e32 v19, 0x5a, v17
	v_cndmask_b32_e32 v13, v183, v13, vcc
	v_cmp_gt_u32_e32 vcc, s27, v19
	v_cmp_gt_u32_e64 s[42:43], s18, v18
	s_and_b64 vcc, s[42:43], vcc
	v_or_b32_e32 v16, 27, v16
	v_add_u32_e32 v17, 0x5b, v17
	v_cndmask_b32_e32 v14, v183, v14, vcc
	v_cmp_gt_u32_e32 vcc, s27, v17
	v_cmp_gt_u32_e64 s[42:43], s18, v16
	v_max_f32_e32 v16, v1, v1
	v_max_f32_e32 v17, v0, v0
	v_max_f32_e32 v16, v17, v16
	v_max3_f32 v16, v16, v2, v3
	v_max3_f32 v16, v16, v4, v5
	v_max3_f32 v16, v16, v6, v7
	v_max3_f32 v16, v16, v8, v9
	s_and_b64 vcc, s[42:43], vcc
	v_max3_f32 v16, v16, v10, v11
	v_cndmask_b32_e32 v15, v183, v15, vcc
	v_max3_f32 v16, v16, v12, v13
	v_max3_f32 v16, v16, v14, v15
	ds_bpermute_b32 v17, v99, v16
	s_waitcnt lgkmcnt(0)
	v_max3_f32 v64, v16, v17, s19
	v_sub_f32_e32 v0, v0, v64
	v_exp_f32_e32 v17, v0
	v_sub_f32_e32 v0, v1, v64
	v_exp_f32_e32 v18, v0
	v_sub_f32_e32 v0, v2, v64
	v_exp_f32_e32 v19, v0
	v_sub_f32_e32 v0, v3, v64
	v_sub_f32_e32 v16, 0xf149f2ca, v64
	v_exp_f32_e32 v20, v0
	v_sub_f32_e32 v0, v4, v64
	v_exp_f32_e32 v23, v0
	v_sub_f32_e32 v0, v5, v64
	v_exp_f32_e32 v65, v16
	v_add_f32_e32 v16, 0, v17
	v_exp_f32_e32 v24, v0
	v_sub_f32_e32 v0, v6, v64
	v_add_f32_e32 v16, v18, v16
	v_exp_f32_e32 v25, v0
	v_sub_f32_e32 v0, v7, v64
	v_add_f32_e32 v16, v19, v16
	v_exp_f32_e32 v26, v0
	v_sub_f32_e32 v0, v8, v64
	v_add_f32_e32 v16, v20, v16
	v_exp_f32_e32 v40, v0
	v_sub_f32_e32 v0, v9, v64
	v_add_f32_e32 v16, v23, v16
	v_exp_f32_e32 v41, v0
	v_sub_f32_e32 v0, v10, v64
	v_add_f32_e32 v16, v24, v16
	v_exp_f32_e32 v42, v0
	v_sub_f32_e32 v0, v11, v64
	v_add_f32_e32 v16, v25, v16
	v_exp_f32_e32 v43, v0
	v_sub_f32_e32 v0, v12, v64
	v_add_f32_e32 v16, v26, v16
	v_exp_f32_e32 v44, v0
	v_sub_f32_e32 v0, v13, v64
	v_add_f32_e32 v16, v40, v16
	v_exp_f32_e32 v45, v0
	v_sub_f32_e32 v0, v14, v64
	v_add_f32_e32 v16, v41, v16
	v_exp_f32_e32 v46, v0
	v_sub_f32_e32 v0, v15, v64
	v_add_f32_e32 v16, v42, v16
	v_exp_f32_e32 v47, v0
	v_add_f32_e32 v16, v43, v16
	v_add_f32_e32 v16, v44, v16
	v_add_f32_e32 v16, v45, v16
	v_add_f32_e32 v16, v46, v16
	v_add_f32_e32 v71, v47, v16
	v_or_b32_e32 v16, v104, v102
	v_lshlrev_b32_e32 v66, 6, v16
	v_or_b32_e32 v67, v66, v100
	v_or3_b32 v16, v66, s24, v100
	ds_read_b64_tr_b16 v[36:37], v67 offset:49152
	ds_read_b64_tr_b16 v[38:39], v16 offset:49152
	v_mul_f32_e32 v0, 0, v65
	v_mov_b32_e32 v1, v0
	v_mov_b32_e32 v2, v0
	v_mov_b32_e32 v3, v0
	v_mov_b32_e32 v4, v0
	v_mov_b32_e32 v5, v0
	v_mov_b32_e32 v6, v0
	v_mov_b32_e32 v7, v0
	v_mov_b32_e32 v8, v0
	v_mov_b32_e32 v9, v0
	v_mov_b32_e32 v10, v0
	v_mov_b32_e32 v11, v0
	v_mov_b32_e32 v12, v0
	v_mov_b32_e32 v13, v0
	v_mov_b32_e32 v14, v0
	v_mov_b32_e32 v15, v0
	v_cvt_pk_bf16_f32 v32, v17, v18
	v_cvt_pk_bf16_f32 v33, v19, v20
	v_cvt_pk_bf16_f32 v34, v23, v24
	v_cvt_pk_bf16_f32 v35, v25, v26
	s_movk_i32 s19, 0x400
	v_fmac_f32_e32 v71, 0, v65
	s_waitcnt lgkmcnt(0)
	v_mfma_f32_32x32x16_bf16 v[16:31], v[36:39], v[32:35], v[0:15]
	v_add_u32_e32 v36, 0x12000, v67
	v_add_u32_e32 v38, 0x12200, v67
	ds_read_b64_tr_b16 v[36:37], v36
	ds_read_b64_tr_b16 v[38:39], v38
	s_waitcnt lgkmcnt(0)
	v_mfma_f32_32x32x16_bf16 v[0:15], v[36:39], v[32:35], v[0:15]
	v_or3_b32 v36, v66, s19, v100
	v_or3_b32 v38, v66, s26, v100
	ds_read_b64_tr_b16 v[36:37], v36 offset:49152
	ds_read_b64_tr_b16 v[38:39], v38 offset:49152
	v_cvt_pk_bf16_f32 v32, v40, v41
	v_cvt_pk_bf16_f32 v33, v42, v43
	v_cvt_pk_bf16_f32 v34, v44, v45
	v_cvt_pk_bf16_f32 v35, v46, v47
	s_waitcnt lgkmcnt(0)
	s_nop 0
	v_mfma_f32_32x32x16_bf16 v[16:31], v[36:39], v[32:35], v[16:31]
	v_add_u32_e32 v36, 0x12400, v67
	v_add_u32_e32 v38, 0x12600, v67
	ds_read_b64_tr_b16 v[36:37], v36
	ds_read_b64_tr_b16 v[38:39], v38
	s_waitcnt lgkmcnt(0)
	v_mfma_f32_32x32x16_bf16 v[0:15], v[36:39], v[32:35], v[0:15]
	v_or_b32_e32 v32, v73, v195
	v_lshlrev_b32_e32 v65, 7, v32
	v_or_b32_e32 v32, v65, v108
	ds_read_b128 v[32:35], v32
	v_or_b32_e32 v66, v65, v107
	ds_read_b128 v[66:69], v66
	s_waitcnt lgkmcnt(1)
	v_mfma_f32_32x32x16_bf16 v[32:47], v[32:35], v[60:63], 0
	s_waitcnt lgkmcnt(0)
	v_mfma_f32_32x32x16_bf16 v[32:47], v[66:69], v[52:55], v[32:47]
	v_or_b32_e32 v66, v65, v106
	ds_read_b128 v[66:69], v66
	v_or_b32_e32 v65, v65, v105
	s_waitcnt lgkmcnt(0)
	v_mfma_f32_32x32x16_bf16 v[32:47], v[66:69], v[56:59], v[32:47]
	ds_read_b128 v[66:69], v65
	v_add_u32_e32 v65, v103, v73
	v_cmp_gt_u32_e64 s[42:43], s18, v65
	s_waitcnt lgkmcnt(0)
	v_mfma_f32_32x32x16_bf16 v[32:47], v[66:69], v[48:51], v[32:47]
	v_sub_u32_e32 v66, v65, v101
	v_add_u32_e32 v67, 64, v66
	v_cmp_gt_u32_e32 vcc, s27, v67
	s_and_b64 vcc, s[42:43], vcc
	v_or_b32_e32 v67, 1, v65
	v_add_u32_e32 v68, 0x41, v66
	v_cmp_gt_u32_e64 s[42:43], s18, v67
	s_nop 4
	v_cndmask_b32_e32 v32, v183, v32, vcc
	v_cmp_gt_u32_e32 vcc, s27, v68
	s_and_b64 vcc, s[42:43], vcc
	v_or_b32_e32 v67, 2, v65
	v_add_u32_e32 v68, 0x42, v66
	v_cndmask_b32_e32 v33, v183, v33, vcc
	v_cmp_gt_u32_e32 vcc, s27, v68
	v_cmp_gt_u32_e64 s[42:43], s18, v67
	s_and_b64 vcc, s[42:43], vcc
	v_or_b32_e32 v67, 3, v65
	v_add_u32_e32 v68, 0x43, v66
	v_cndmask_b32_e32 v34, v183, v34, vcc
	v_cmp_gt_u32_e32 vcc, s27, v68
	v_cmp_gt_u32_e64 s[42:43], s18, v67
	s_and_b64 vcc, s[42:43], vcc
	v_or_b32_e32 v67, 8, v65
	v_add_u32_e32 v68, 0x48, v66
	v_cndmask_b32_e32 v35, v183, v35, vcc
	v_cmp_gt_u32_e32 vcc, s27, v68
	v_cmp_gt_u32_e64 s[42:43], s18, v67
	s_and_b64 vcc, s[42:43], vcc
	v_or_b32_e32 v67, 9, v65
	v_add_u32_e32 v68, 0x49, v66
	v_cndmask_b32_e32 v36, v183, v36, vcc
	v_cmp_gt_u32_e32 vcc, s27, v68
	v_cmp_gt_u32_e64 s[42:43], s18, v67
	s_and_b64 vcc, s[42:43], vcc
	v_or_b32_e32 v67, 10, v65
	v_add_u32_e32 v68, 0x4a, v66
	v_cndmask_b32_e32 v37, v183, v37, vcc
	v_cmp_gt_u32_e32 vcc, s27, v68
	v_cmp_gt_u32_e64 s[42:43], s18, v67
	s_and_b64 vcc, s[42:43], vcc
	v_or_b32_e32 v67, 11, v65
	v_add_u32_e32 v68, 0x4b, v66
	v_cndmask_b32_e32 v38, v183, v38, vcc
	v_cmp_gt_u32_e32 vcc, s27, v68
	v_cmp_gt_u32_e64 s[42:43], s18, v67
	s_and_b64 vcc, s[42:43], vcc
	v_or_b32_e32 v67, 16, v65
	v_add_u32_e32 v68, 0x50, v66
	v_cndmask_b32_e32 v39, v183, v39, vcc
	v_cmp_gt_u32_e32 vcc, s27, v68
	v_cmp_gt_u32_e64 s[42:43], s18, v67
	s_and_b64 vcc, s[42:43], vcc
	v_or_b32_e32 v67, 17, v65
	v_add_u32_e32 v68, 0x51, v66
	v_cndmask_b32_e32 v40, v183, v40, vcc
	v_cmp_gt_u32_e32 vcc, s27, v68
	v_cmp_gt_u32_e64 s[42:43], s18, v67
	s_and_b64 vcc, s[42:43], vcc
	v_or_b32_e32 v67, 18, v65
	v_add_u32_e32 v68, 0x52, v66
	v_cndmask_b32_e32 v41, v183, v41, vcc
	v_cmp_gt_u32_e32 vcc, s27, v68
	v_cmp_gt_u32_e64 s[42:43], s18, v67
	s_and_b64 vcc, s[42:43], vcc
	v_or_b32_e32 v67, 19, v65
	v_add_u32_e32 v68, 0x53, v66
	v_cndmask_b32_e32 v42, v183, v42, vcc
	v_cmp_gt_u32_e32 vcc, s27, v68
	v_cmp_gt_u32_e64 s[42:43], s18, v67
	s_and_b64 vcc, s[42:43], vcc
	v_or_b32_e32 v67, 24, v65
	v_add_u32_e32 v68, 0x58, v66
	v_cndmask_b32_e32 v43, v183, v43, vcc
	v_cmp_gt_u32_e32 vcc, s27, v68
	v_cmp_gt_u32_e64 s[42:43], s18, v67
	s_and_b64 vcc, s[42:43], vcc
	v_or_b32_e32 v67, 25, v65
	v_add_u32_e32 v68, 0x59, v66
	v_cndmask_b32_e32 v44, v183, v44, vcc
	v_cmp_gt_u32_e32 vcc, s27, v68
	v_cmp_gt_u32_e64 s[42:43], s18, v67
	s_and_b64 vcc, s[42:43], vcc
	v_or_b32_e32 v67, 26, v65
	v_add_u32_e32 v68, 0x5a, v66
	v_cndmask_b32_e32 v45, v183, v45, vcc
	v_cmp_gt_u32_e32 vcc, s27, v68
	v_cmp_gt_u32_e64 s[42:43], s18, v67
	s_and_b64 vcc, s[42:43], vcc
	v_or_b32_e32 v65, 27, v65
	v_add_u32_e32 v66, 0x5b, v66
	v_cndmask_b32_e32 v46, v183, v46, vcc
	v_cmp_gt_u32_e32 vcc, s27, v66
	v_cmp_gt_u32_e64 s[42:43], s18, v65
	v_max_f32_e32 v65, v33, v33
	v_max_f32_e32 v66, v32, v32
	v_max_f32_e32 v65, v66, v65
	v_max3_f32 v65, v65, v34, v35
	v_max3_f32 v65, v65, v36, v37
	v_max3_f32 v65, v65, v38, v39
	v_max3_f32 v65, v65, v40, v41
	s_and_b64 vcc, s[42:43], vcc
	v_max3_f32 v65, v65, v42, v43
	v_cndmask_b32_e32 v47, v183, v47, vcc
	v_max3_f32 v65, v65, v44, v45
	v_max3_f32 v65, v65, v46, v47
	ds_bpermute_b32 v66, v99, v65
	s_waitcnt lgkmcnt(0)
	v_max3_f32 v65, v64, v65, v66
	v_sub_f32_e32 v32, v32, v65
	v_exp_f32_e32 v69, v32
	v_sub_f32_e32 v32, v33, v65
	v_exp_f32_e32 v75, v32
	v_sub_f32_e32 v32, v34, v65
	v_exp_f32_e32 v78, v32
	v_sub_f32_e32 v32, v35, v65
	v_exp_f32_e32 v80, v32
	v_sub_f32_e32 v32, v36, v65
	v_exp_f32_e32 v82, v32
	v_sub_f32_e32 v32, v37, v65
	v_exp_f32_e32 v84, v32
	v_sub_f32_e32 v32, v38, v65
	v_exp_f32_e32 v86, v32
	v_sub_f32_e32 v32, v39, v65
	v_exp_f32_e32 v88, v32
	v_sub_f32_e32 v32, v40, v65
	v_exp_f32_e32 v90, v32
	v_sub_f32_e32 v32, v41, v65
	v_exp_f32_e32 v92, v32
	v_sub_f32_e32 v32, v42, v65
	v_sub_f32_e32 v67, v64, v65
	v_exp_f32_e32 v64, v32
	v_sub_f32_e32 v32, v43, v65
	v_exp_f32_e32 v66, v32
	v_sub_f32_e32 v32, v44, v65
	v_exp_f32_e32 v68, v32
	v_sub_f32_e32 v32, v45, v65
	v_exp_f32_e32 v70, v32
	v_sub_f32_e32 v32, v46, v65
	v_exp_f32_e32 v72, v32
	v_sub_f32_e32 v32, v47, v65
	v_exp_f32_e32 v74, v32
	v_exp_f32_e32 v32, v67
	s_nop 0
	v_pk_mul_f32 v[36:37], v[4:5], v[32:33] op_sel_hi:[1,0]
	v_or_b32_e32 v4, v104, v73
	v_pk_mul_f32 v[40:41], v[8:9], v[32:33] op_sel_hi:[1,0]
	v_lshlrev_b32_e32 v8, 6, v4
	v_pk_mul_f32 v[38:39], v[6:7], v[32:33] op_sel_hi:[1,0]
	v_or3_b32 v6, v8, s24, v100
	v_or_b32_e32 v9, v8, v100
	ds_read_b64_tr_b16 v[4:5], v9 offset:49152
	ds_read_b64_tr_b16 v[6:7], v6 offset:49152
	v_mul_f32_e32 v76, v71, v32
	v_pk_mul_f32 v[30:31], v[30:31], v[32:33] op_sel_hi:[1,0]
	v_pk_mul_f32 v[28:29], v[28:29], v[32:33] op_sel_hi:[1,0]
	v_pk_mul_f32 v[26:27], v[26:27], v[32:33] op_sel_hi:[1,0]
	v_pk_mul_f32 v[24:25], v[24:25], v[32:33] op_sel_hi:[1,0]
	v_pk_mul_f32 v[22:23], v[22:23], v[32:33] op_sel_hi:[1,0]
	v_pk_mul_f32 v[20:21], v[20:21], v[32:33] op_sel_hi:[1,0]
	v_pk_mul_f32 v[18:19], v[18:19], v[32:33] op_sel_hi:[1,0]
	v_pk_mul_f32 v[16:17], v[16:17], v[32:33] op_sel_hi:[1,0]
	v_pk_mul_f32 v[46:47], v[14:15], v[32:33] op_sel_hi:[1,0]
	v_pk_mul_f32 v[44:45], v[12:13], v[32:33] op_sel_hi:[1,0]
	v_pk_mul_f32 v[42:43], v[10:11], v[32:33] op_sel_hi:[1,0]
	v_pk_mul_f32 v[34:35], v[2:3], v[32:33] op_sel_hi:[1,0]
	v_pk_mul_f32 v[32:33], v[0:1], v[32:33] op_sel_hi:[1,0]
	v_add_f32_e32 v0, 0, v69
	v_add_f32_e32 v94, v75, v0
	v_cvt_pk_bf16_f32 v0, v69, v75
	v_cvt_pk_bf16_f32 v1, v78, v80
	v_cvt_pk_bf16_f32 v2, v82, v84
	v_cvt_pk_bf16_f32 v3, v86, v88
	s_waitcnt lgkmcnt(0)
	s_nop 0
	v_mfma_f32_32x32x16_bf16 v[16:31], v[4:7], v[0:3], v[16:31]
	v_add_u32_e32 v4, 0x12000, v9
	v_add_u32_e32 v6, 0x12200, v9
	ds_read_b64_tr_b16 v[4:5], v4
	ds_read_b64_tr_b16 v[6:7], v6
	s_waitcnt lgkmcnt(0)
	v_mfma_f32_32x32x16_bf16 v[32:47], v[4:7], v[0:3], v[32:47]
	v_or3_b32 v4, v8, s19, v100
	v_or3_b32 v6, v8, s26, v100
	ds_read_b64_tr_b16 v[4:5], v4 offset:49152
	ds_read_b64_tr_b16 v[6:7], v6 offset:49152
	v_cvt_pk_bf16_f32 v0, v90, v92
	v_cvt_pk_bf16_f32 v1, v64, v66
	v_cvt_pk_bf16_f32 v2, v68, v70
	v_cvt_pk_bf16_f32 v3, v72, v74
	s_waitcnt lgkmcnt(0)
	s_nop 0
	v_mfma_f32_32x32x16_bf16 v[16:31], v[4:7], v[0:3], v[16:31]
	v_add_u32_e32 v4, 0x12400, v9
	v_add_u32_e32 v6, 0x12600, v9
	ds_read_b64_tr_b16 v[4:5], v4
	ds_read_b64_tr_b16 v[6:7], v6
	s_waitcnt lgkmcnt(0)
	v_mfma_f32_32x32x16_bf16 v[32:47], v[4:7], v[0:3], v[32:47]
	v_or_b32_e32 v0, v114, v195
	v_lshlrev_b32_e32 v67, 7, v0
	v_or_b32_e32 v0, v67, v108
	ds_read_b128 v[0:3], v0
	v_or_b32_e32 v69, v67, v107
	ds_read_b128 v[110:113], v69
	v_or_b32_e32 v69, v67, v106
	s_waitcnt lgkmcnt(1)
	v_mfma_f32_32x32x16_bf16 v[0:15], v[0:3], v[60:63], 0
	v_or_b32_e32 v67, v67, v105
	s_waitcnt lgkmcnt(0)
	v_mfma_f32_32x32x16_bf16 v[0:15], v[110:113], v[52:55], v[0:15]
	ds_read_b128 v[110:113], v69
	s_waitcnt lgkmcnt(0)
	v_mfma_f32_32x32x16_bf16 v[0:15], v[110:113], v[56:59], v[0:15]
	ds_read_b128 v[110:113], v67
	v_add_u32_e32 v67, v103, v114
	v_sub_u32_e32 v69, v67, v101
	v_add_u32_e32 v71, 64, v69
	v_cmp_gt_u32_e32 vcc, s27, v71
	v_cmp_gt_u32_e64 s[42:43], s18, v67
	s_and_b64 vcc, s[42:43], vcc
	s_waitcnt lgkmcnt(0)
	v_mfma_f32_32x32x16_bf16 v[0:15], v[110:113], v[48:51], v[0:15]
	v_or_b32_e32 v71, 1, v67
	v_add_u32_e32 v73, 0x41, v69
	v_cmp_gt_u32_e64 s[42:43], s18, v71
	v_or_b32_e32 v71, 2, v67
	s_nop 7
	v_cndmask_b32_e32 v0, v183, v0, vcc
	v_cmp_gt_u32_e32 vcc, s27, v73
	s_and_b64 vcc, s[42:43], vcc
	v_add_u32_e32 v73, 0x42, v69
	v_cndmask_b32_e32 v1, v183, v1, vcc
	v_cmp_gt_u32_e32 vcc, s27, v73
	v_cmp_gt_u32_e64 s[42:43], s18, v71
	s_and_b64 vcc, s[42:43], vcc
	v_or_b32_e32 v71, 3, v67
	v_add_u32_e32 v73, 0x43, v69
	v_cndmask_b32_e32 v2, v183, v2, vcc
	v_cmp_gt_u32_e32 vcc, s27, v73
	v_cmp_gt_u32_e64 s[42:43], s18, v71
	s_and_b64 vcc, s[42:43], vcc
	v_or_b32_e32 v71, 8, v67
	v_add_u32_e32 v73, 0x48, v69
	v_cndmask_b32_e32 v3, v183, v3, vcc
	v_cmp_gt_u32_e32 vcc, s27, v73
	v_cmp_gt_u32_e64 s[42:43], s18, v71
	s_and_b64 vcc, s[42:43], vcc
	v_or_b32_e32 v71, 9, v67
	v_add_u32_e32 v73, 0x49, v69
	v_cndmask_b32_e32 v4, v183, v4, vcc
	v_cmp_gt_u32_e32 vcc, s27, v73
	v_cmp_gt_u32_e64 s[42:43], s18, v71
	s_and_b64 vcc, s[42:43], vcc
	v_or_b32_e32 v71, 10, v67
	v_add_u32_e32 v73, 0x4a, v69
	v_cndmask_b32_e32 v5, v183, v5, vcc
	v_cmp_gt_u32_e32 vcc, s27, v73
	v_cmp_gt_u32_e64 s[42:43], s18, v71
	s_and_b64 vcc, s[42:43], vcc
	v_or_b32_e32 v71, 11, v67
	v_add_u32_e32 v73, 0x4b, v69
	v_cndmask_b32_e32 v6, v183, v6, vcc
	v_cmp_gt_u32_e32 vcc, s27, v73
	v_cmp_gt_u32_e64 s[42:43], s18, v71
	s_and_b64 vcc, s[42:43], vcc
	v_or_b32_e32 v71, 16, v67
	v_add_u32_e32 v73, 0x50, v69
	v_cndmask_b32_e32 v7, v183, v7, vcc
	v_cmp_gt_u32_e32 vcc, s27, v73
	v_cmp_gt_u32_e64 s[42:43], s18, v71
	s_and_b64 vcc, s[42:43], vcc
	v_or_b32_e32 v71, 17, v67
	v_add_u32_e32 v73, 0x51, v69
	v_cndmask_b32_e32 v8, v183, v8, vcc
	v_cmp_gt_u32_e32 vcc, s27, v73
	v_cmp_gt_u32_e64 s[42:43], s18, v71
	s_and_b64 vcc, s[42:43], vcc
	v_or_b32_e32 v71, 18, v67
	v_add_u32_e32 v73, 0x52, v69
	v_cndmask_b32_e32 v9, v183, v9, vcc
	v_cmp_gt_u32_e32 vcc, s27, v73
	v_cmp_gt_u32_e64 s[42:43], s18, v71
	s_and_b64 vcc, s[42:43], vcc
	v_or_b32_e32 v71, 19, v67
	v_add_u32_e32 v73, 0x53, v69
	v_cndmask_b32_e32 v10, v183, v10, vcc
	v_cmp_gt_u32_e32 vcc, s27, v73
	v_cmp_gt_u32_e64 s[42:43], s18, v71
	s_and_b64 vcc, s[42:43], vcc
	v_or_b32_e32 v71, 24, v67
	v_add_u32_e32 v73, 0x58, v69
	v_cndmask_b32_e32 v11, v183, v11, vcc
	v_cmp_gt_u32_e32 vcc, s27, v73
	v_cmp_gt_u32_e64 s[42:43], s18, v71
	s_and_b64 vcc, s[42:43], vcc
	v_or_b32_e32 v71, 25, v67
	v_add_u32_e32 v73, 0x59, v69
	v_cndmask_b32_e32 v12, v183, v12, vcc
	v_cmp_gt_u32_e32 vcc, s27, v73
	v_cmp_gt_u32_e64 s[42:43], s18, v71
	s_and_b64 vcc, s[42:43], vcc
	v_or_b32_e32 v71, 26, v67
	v_add_u32_e32 v73, 0x5a, v69
	v_cndmask_b32_e32 v13, v183, v13, vcc
	v_cmp_gt_u32_e32 vcc, s27, v73
	v_cmp_gt_u32_e64 s[42:43], s18, v71
	s_and_b64 vcc, s[42:43], vcc
	v_or_b32_e32 v67, 27, v67
	v_add_u32_e32 v69, 0x5b, v69
	v_cndmask_b32_e32 v14, v183, v14, vcc
	v_cmp_gt_u32_e32 vcc, s27, v69
	v_cmp_gt_u32_e64 s[42:43], s18, v67
	v_max_f32_e32 v67, v1, v1
	v_max_f32_e32 v69, v0, v0
	v_max_f32_e32 v67, v69, v67
	v_max3_f32 v67, v67, v2, v3
	v_max3_f32 v67, v67, v4, v5
	v_max3_f32 v67, v67, v6, v7
	v_max3_f32 v67, v67, v8, v9
	s_and_b64 vcc, s[42:43], vcc
	v_max3_f32 v67, v67, v10, v11
	v_cndmask_b32_e32 v15, v183, v15, vcc
	v_max3_f32 v67, v67, v12, v13
	v_max3_f32 v67, v67, v14, v15
	ds_bpermute_b32 v69, v99, v67
	s_waitcnt lgkmcnt(0)
	v_max3_f32 v109, v65, v67, v69
	v_sub_f32_e32 v0, v0, v109
	v_exp_f32_e32 v79, v0
	v_sub_f32_e32 v0, v1, v109
	v_exp_f32_e32 v81, v0
	v_sub_f32_e32 v0, v2, v109
	v_exp_f32_e32 v83, v0
	v_sub_f32_e32 v0, v3, v109
	v_exp_f32_e32 v85, v0
	v_sub_f32_e32 v0, v4, v109
	v_exp_f32_e32 v87, v0
	v_sub_f32_e32 v0, v5, v109
	v_exp_f32_e32 v89, v0
	v_sub_f32_e32 v0, v6, v109
	v_exp_f32_e32 v91, v0
	v_sub_f32_e32 v0, v7, v109
	v_exp_f32_e32 v93, v0
	v_sub_f32_e32 v0, v8, v109
	v_sub_f32_e32 v95, v65, v109
	v_exp_f32_e32 v65, v0
	v_sub_f32_e32 v0, v9, v109
	v_exp_f32_e32 v67, v0
	v_sub_f32_e32 v0, v10, v109
	v_exp_f32_e32 v69, v0
	v_sub_f32_e32 v0, v11, v109
	v_exp_f32_e32 v71, v0
	v_sub_f32_e32 v0, v12, v109
	v_exp_f32_e32 v96, v95
	v_exp_f32_e32 v73, v0
	v_sub_f32_e32 v0, v13, v109
	v_exp_f32_e32 v75, v0
	v_sub_f32_e32 v0, v14, v109
	v_exp_f32_e32 v77, v0
	v_sub_f32_e32 v0, v15, v109
	v_mov_b32_e32 v95, v169
	v_exp_f32_e32 v110, v0
	v_pk_mul_f32 v[0:1], v[16:17], v[96:97] op_sel_hi:[1,0]
	v_pk_mul_f32 v[16:17], v[32:33], v[96:97] op_sel_hi:[1,0]
	v_pk_add_f32 v[32:33], v[78:79], v[94:95]
	v_pk_mul_f32 v[6:7], v[22:23], v[96:97] op_sel_hi:[1,0]
	v_pk_add_f32 v[32:33], v[80:81], v[32:33]
	v_pk_mul_f32 v[22:23], v[38:39], v[96:97] op_sel_hi:[1,0]
	v_pk_add_f32 v[32:33], v[82:83], v[32:33]
	v_or_b32_e32 v38, v104, v114
	v_pk_add_f32 v[32:33], v[84:85], v[32:33]
	v_pk_mul_f32 v[10:11], v[26:27], v[96:97] op_sel_hi:[1,0]
	v_pk_add_f32 v[32:33], v[86:87], v[32:33]
	v_pk_mul_f32 v[26:27], v[42:43], v[96:97] op_sel_hi:[1,0]
	v_pk_add_f32 v[32:33], v[88:89], v[32:33]
	v_lshlrev_b32_e32 v42, 6, v38
	v_pk_add_f32 v[32:33], v[90:91], v[32:33]
	v_pk_mul_f32 v[8:9], v[24:25], v[96:97] op_sel_hi:[1,0]
	v_pk_add_f32 v[32:33], v[92:93], v[32:33]
	v_pk_mul_f32 v[24:25], v[40:41], v[96:97] op_sel_hi:[1,0]
	v_pk_add_f32 v[32:33], v[64:65], v[32:33]
	v_or3_b32 v40, v42, s24, v100
	v_pk_add_f32 v[32:33], v[66:67], v[32:33]
	v_or_b32_e32 v43, v42, v100
	v_pk_add_f32 v[32:33], v[68:69], v[32:33]
	ds_read_b64_tr_b16 v[38:39], v43 offset:49152
	ds_read_b64_tr_b16 v[40:41], v40 offset:49152
	v_pk_add_f32 v[32:33], v[70:71], v[32:33]
	v_pk_mul_f32 v[14:15], v[30:31], v[96:97] op_sel_hi:[1,0]
	v_pk_add_f32 v[32:33], v[72:73], v[32:33]
	v_pk_mul_f32 v[12:13], v[28:29], v[96:97] op_sel_hi:[1,0]
	v_pk_add_f32 v[32:33], v[74:75], v[32:33]
	v_pk_mul_f32 v[4:5], v[20:21], v[96:97] op_sel_hi:[1,0]
	v_pk_mul_f32 v[2:3], v[18:19], v[96:97] op_sel_hi:[1,0]
	v_pk_mul_f32 v[20:21], v[36:37], v[96:97] op_sel_hi:[1,0]
	v_pk_mul_f32 v[18:19], v[34:35], v[96:97] op_sel_hi:[1,0]
	v_pk_add_f32 v[36:37], v[76:77], v[32:33]
	v_cvt_pk_bf16_f32 v32, v79, v81
	v_cvt_pk_bf16_f32 v33, v83, v85
	v_cvt_pk_bf16_f32 v34, v87, v89
	v_cvt_pk_bf16_f32 v35, v91, v93
	v_pk_mul_f32 v[30:31], v[46:47], v[96:97] op_sel_hi:[1,0]
	v_pk_mul_f32 v[28:29], v[44:45], v[96:97] op_sel_hi:[1,0]
	s_waitcnt lgkmcnt(0)
	v_mfma_f32_32x32x16_bf16 v[0:15], v[38:41], v[32:35], v[0:15]
	v_add_u32_e32 v38, 0x12000, v43
	v_add_u32_e32 v40, 0x12200, v43
	ds_read_b64_tr_b16 v[38:39], v38
	ds_read_b64_tr_b16 v[40:41], v40
	s_waitcnt lgkmcnt(0)
	v_mfma_f32_32x32x16_bf16 v[16:31], v[38:41], v[32:35], v[16:31]
	v_or3_b32 v38, v42, s19, v100
	v_or3_b32 v40, v42, s26, v100
	ds_read_b64_tr_b16 v[38:39], v38 offset:49152
	ds_read_b64_tr_b16 v[40:41], v40 offset:49152
	v_cvt_pk_bf16_f32 v32, v65, v67
	v_cvt_pk_bf16_f32 v33, v69, v71
	v_cvt_pk_bf16_f32 v34, v73, v75
	v_cvt_pk_bf16_f32 v35, v77, v110
	v_add_u32_e32 v71, 0x60, v102
	v_add_f32_e32 v69, v37, v110
	s_waitcnt lgkmcnt(0)
	v_mfma_f32_32x32x16_bf16 v[0:15], v[38:41], v[32:35], v[0:15]
	v_add_u32_e32 v38, 0x12400, v43
	v_add_u32_e32 v40, 0x12600, v43
	ds_read_b64_tr_b16 v[38:39], v38
	ds_read_b64_tr_b16 v[40:41], v40
	v_fmac_f32_e32 v69, v36, v96
	v_add_u32_e32 v96, 0x80, v102
	s_waitcnt lgkmcnt(0)
	v_mfma_f32_32x32x16_bf16 v[16:31], v[38:41], v[32:35], v[16:31]
	v_or_b32_e32 v32, v71, v195
	v_lshlrev_b32_e32 v68, 7, v32
	v_or_b32_e32 v32, v68, v108
	ds_read_b128 v[32:35], v32
	v_or_b32_e32 v64, v68, v107
	ds_read_b128 v[64:67], v64
	s_waitcnt lgkmcnt(1)
	v_mfma_f32_32x32x16_bf16 v[32:47], v[32:35], v[60:63], 0
	s_waitcnt lgkmcnt(0)
	v_mfma_f32_32x32x16_bf16 v[32:47], v[64:67], v[52:55], v[32:47]
	v_or_b32_e32 v64, v68, v106
	ds_read_b128 v[64:67], v64
	s_waitcnt lgkmcnt(0)
	v_mfma_f32_32x32x16_bf16 v[32:47], v[64:67], v[56:59], v[32:47]
	v_or_b32_e32 v64, v68, v105
	ds_read_b128 v[64:67], v64
	s_waitcnt lgkmcnt(0)
	v_mfma_f32_32x32x16_bf16 v[32:47], v[64:67], v[48:51], v[32:47]
	v_add_u32_e32 v64, v103, v71
	v_sub_u32_e32 v65, v64, v101
	v_add_u32_e32 v66, 64, v65
	v_cmp_gt_u32_e32 vcc, s27, v66
	v_cmp_gt_u32_e64 s[42:43], s18, v64
	s_and_b64 vcc, s[42:43], vcc
	v_or_b32_e32 v66, 1, v64
	v_add_u32_e32 v67, 0x41, v65
	s_nop 3
	v_cndmask_b32_e32 v32, v183, v32, vcc
	v_cmp_gt_u32_e32 vcc, s27, v67
	v_cmp_gt_u32_e64 s[42:43], s18, v66
	s_and_b64 vcc, s[42:43], vcc
	v_or_b32_e32 v66, 2, v64
	v_add_u32_e32 v67, 0x42, v65
	v_cndmask_b32_e32 v33, v183, v33, vcc
	v_cmp_gt_u32_e32 vcc, s27, v67
	v_cmp_gt_u32_e64 s[42:43], s18, v66
	s_and_b64 vcc, s[42:43], vcc
	v_or_b32_e32 v66, 3, v64
	v_add_u32_e32 v67, 0x43, v65
	v_cndmask_b32_e32 v34, v183, v34, vcc
	v_cmp_gt_u32_e32 vcc, s27, v67
	v_cmp_gt_u32_e64 s[42:43], s18, v66
	s_and_b64 vcc, s[42:43], vcc
	v_or_b32_e32 v66, 8, v64
	v_add_u32_e32 v67, 0x48, v65
	v_cndmask_b32_e32 v35, v183, v35, vcc
	v_cmp_gt_u32_e32 vcc, s27, v67
	v_cmp_gt_u32_e64 s[42:43], s18, v66
	s_and_b64 vcc, s[42:43], vcc
	v_or_b32_e32 v66, 9, v64
	v_add_u32_e32 v67, 0x49, v65
	v_cndmask_b32_e32 v36, v183, v36, vcc
	v_cmp_gt_u32_e32 vcc, s27, v67
	v_cmp_gt_u32_e64 s[42:43], s18, v66
	s_and_b64 vcc, s[42:43], vcc
	v_or_b32_e32 v66, 10, v64
	v_add_u32_e32 v67, 0x4a, v65
	v_cndmask_b32_e32 v37, v183, v37, vcc
	v_cmp_gt_u32_e32 vcc, s27, v67
	v_cmp_gt_u32_e64 s[42:43], s18, v66
	s_and_b64 vcc, s[42:43], vcc
	v_or_b32_e32 v66, 11, v64
	v_add_u32_e32 v67, 0x4b, v65
	v_cndmask_b32_e32 v38, v183, v38, vcc
	v_cmp_gt_u32_e32 vcc, s27, v67
	v_cmp_gt_u32_e64 s[42:43], s18, v66
	s_and_b64 vcc, s[42:43], vcc
	v_or_b32_e32 v66, 16, v64
	v_add_u32_e32 v67, 0x50, v65
	v_cndmask_b32_e32 v39, v183, v39, vcc
	v_cmp_gt_u32_e32 vcc, s27, v67
	v_cmp_gt_u32_e64 s[42:43], s18, v66
	s_and_b64 vcc, s[42:43], vcc
	v_or_b32_e32 v66, 17, v64
	v_add_u32_e32 v67, 0x51, v65
	v_cndmask_b32_e32 v40, v183, v40, vcc
	v_cmp_gt_u32_e32 vcc, s27, v67
	v_cmp_gt_u32_e64 s[42:43], s18, v66
	s_and_b64 vcc, s[42:43], vcc
	v_or_b32_e32 v66, 18, v64
	v_add_u32_e32 v67, 0x52, v65
	v_cndmask_b32_e32 v41, v183, v41, vcc
	v_cmp_gt_u32_e32 vcc, s27, v67
	v_cmp_gt_u32_e64 s[42:43], s18, v66
	s_and_b64 vcc, s[42:43], vcc
	v_or_b32_e32 v66, 19, v64
	v_add_u32_e32 v67, 0x53, v65
	v_cndmask_b32_e32 v42, v183, v42, vcc
	v_cmp_gt_u32_e32 vcc, s27, v67
	v_cmp_gt_u32_e64 s[42:43], s18, v66
	s_and_b64 vcc, s[42:43], vcc
	v_or_b32_e32 v66, 24, v64
	v_add_u32_e32 v67, 0x58, v65
	v_cndmask_b32_e32 v43, v183, v43, vcc
	v_cmp_gt_u32_e32 vcc, s27, v67
	v_cmp_gt_u32_e64 s[42:43], s18, v66
	s_and_b64 vcc, s[42:43], vcc
	v_or_b32_e32 v66, 25, v64
	v_add_u32_e32 v67, 0x59, v65
	v_cndmask_b32_e32 v44, v183, v44, vcc
	v_cmp_gt_u32_e32 vcc, s27, v67
	v_cmp_gt_u32_e64 s[42:43], s18, v66
	s_and_b64 vcc, s[42:43], vcc
	v_or_b32_e32 v66, 26, v64
	v_add_u32_e32 v67, 0x5a, v65
	v_cndmask_b32_e32 v45, v183, v45, vcc
	v_cmp_gt_u32_e32 vcc, s27, v67
	v_cmp_gt_u32_e64 s[42:43], s18, v66
	s_and_b64 vcc, s[42:43], vcc
	v_or_b32_e32 v64, 27, v64
	v_add_u32_e32 v65, 0x5b, v65
	v_cndmask_b32_e32 v46, v183, v46, vcc
	v_cmp_gt_u32_e32 vcc, s27, v65
	v_cmp_gt_u32_e64 s[42:43], s18, v64
	v_max_f32_e32 v64, v33, v33
	v_max_f32_e32 v65, v32, v32
	v_max_f32_e32 v64, v65, v64
	v_max3_f32 v64, v64, v34, v35
	v_max3_f32 v64, v64, v36, v37
	v_max3_f32 v64, v64, v38, v39
	v_max3_f32 v64, v64, v40, v41
	s_and_b64 vcc, s[42:43], vcc
	v_max3_f32 v64, v64, v42, v43
	v_cndmask_b32_e32 v47, v183, v47, vcc
	v_max3_f32 v64, v64, v44, v45
	v_max3_f32 v64, v64, v46, v47
	ds_bpermute_b32 v65, v99, v64
	s_waitcnt lgkmcnt(0)
	v_max3_f32 v65, v109, v64, v65
	v_sub_f32_e32 v32, v32, v65
	v_exp_f32_e32 v73, v32
	v_sub_f32_e32 v32, v33, v65
	v_exp_f32_e32 v75, v32
	v_sub_f32_e32 v32, v34, v65
	v_exp_f32_e32 v78, v32
	v_sub_f32_e32 v32, v35, v65
	v_exp_f32_e32 v80, v32
	v_sub_f32_e32 v32, v36, v65
	v_sub_f32_e32 v67, v109, v65
	v_exp_f32_e32 v82, v32
	v_sub_f32_e32 v32, v37, v65
	v_exp_f32_e32 v84, v32
	v_sub_f32_e32 v32, v38, v65
	v_exp_f32_e32 v94, v67
	v_exp_f32_e32 v86, v32
	v_sub_f32_e32 v32, v39, v65
	v_exp_f32_e32 v88, v32
	v_sub_f32_e32 v32, v40, v65
	v_exp_f32_e32 v90, v32
	v_sub_f32_e32 v32, v41, v65
	v_exp_f32_e32 v92, v32
	v_sub_f32_e32 v32, v42, v65
	v_pk_mul_f32 v[36:37], v[4:5], v[94:95] op_sel_hi:[1,0]
	v_pk_mul_f32 v[4:5], v[20:21], v[94:95] op_sel_hi:[1,0]
	v_or_b32_e32 v20, v104, v71
	v_exp_f32_e32 v64, v32
	v_sub_f32_e32 v32, v43, v65
	v_pk_mul_f32 v[40:41], v[8:9], v[94:95] op_sel_hi:[1,0]
	v_pk_mul_f32 v[8:9], v[24:25], v[94:95] op_sel_hi:[1,0]
	v_lshlrev_b32_e32 v24, 6, v20
	v_exp_f32_e32 v66, v32
	v_sub_f32_e32 v32, v44, v65
	v_pk_mul_f32 v[38:39], v[6:7], v[94:95] op_sel_hi:[1,0]
	v_pk_mul_f32 v[6:7], v[22:23], v[94:95] op_sel_hi:[1,0]
	v_or3_b32 v22, v24, s24, v100
	v_or_b32_e32 v25, v24, v100
	v_exp_f32_e32 v68, v32
	v_sub_f32_e32 v32, v45, v65
	ds_read_b64_tr_b16 v[20:21], v25 offset:49152
	ds_read_b64_tr_b16 v[22:23], v22 offset:49152
	v_exp_f32_e32 v70, v32
	v_sub_f32_e32 v32, v46, v65
	v_exp_f32_e32 v72, v32
	v_sub_f32_e32 v32, v47, v65
	v_exp_f32_e32 v74, v32
	v_pk_mul_f32 v[32:33], v[0:1], v[94:95] op_sel_hi:[1,0]
	v_pk_mul_f32 v[0:1], v[16:17], v[94:95] op_sel_hi:[1,0]
	v_add_f32_e32 v16, 0, v73
	v_mul_f32_e32 v76, v69, v94
	v_pk_mul_f32 v[46:47], v[14:15], v[94:95] op_sel_hi:[1,0]
	v_pk_mul_f32 v[44:45], v[12:13], v[94:95] op_sel_hi:[1,0]
	v_pk_mul_f32 v[42:43], v[10:11], v[94:95] op_sel_hi:[1,0]
	v_pk_mul_f32 v[34:35], v[2:3], v[94:95] op_sel_hi:[1,0]
	v_pk_mul_f32 v[14:15], v[30:31], v[94:95] op_sel_hi:[1,0]
	v_pk_mul_f32 v[12:13], v[28:29], v[94:95] op_sel_hi:[1,0]
	v_pk_mul_f32 v[10:11], v[26:27], v[94:95] op_sel_hi:[1,0]
	v_pk_mul_f32 v[2:3], v[18:19], v[94:95] op_sel_hi:[1,0]
	v_add_f32_e32 v94, v75, v16
	v_cvt_pk_bf16_f32 v16, v73, v75
	v_cvt_pk_bf16_f32 v17, v78, v80
	v_cvt_pk_bf16_f32 v18, v82, v84
	v_cvt_pk_bf16_f32 v19, v86, v88
	s_waitcnt lgkmcnt(0)
	s_nop 0
	v_mfma_f32_32x32x16_bf16 v[32:47], v[20:23], v[16:19], v[32:47]
	v_add_u32_e32 v20, 0x12000, v25
	v_add_u32_e32 v22, 0x12200, v25
	ds_read_b64_tr_b16 v[20:21], v20
	ds_read_b64_tr_b16 v[22:23], v22
	s_waitcnt lgkmcnt(0)
	v_mfma_f32_32x32x16_bf16 v[0:15], v[20:23], v[16:19], v[0:15]
	v_or3_b32 v20, v24, s19, v100
	v_or3_b32 v22, v24, s26, v100
	ds_read_b64_tr_b16 v[20:21], v20 offset:49152
	ds_read_b64_tr_b16 v[22:23], v22 offset:49152
	v_cvt_pk_bf16_f32 v16, v90, v92
	v_cvt_pk_bf16_f32 v17, v64, v66
	v_cvt_pk_bf16_f32 v18, v68, v70
	v_cvt_pk_bf16_f32 v19, v72, v74
	s_waitcnt lgkmcnt(0)
	s_nop 0
	v_mfma_f32_32x32x16_bf16 v[32:47], v[20:23], v[16:19], v[32:47]
	v_add_u32_e32 v20, 0x12400, v25
	v_add_u32_e32 v22, 0x12600, v25
	ds_read_b64_tr_b16 v[20:21], v20
	ds_read_b64_tr_b16 v[22:23], v22
	s_waitcnt lgkmcnt(0)
	v_mfma_f32_32x32x16_bf16 v[0:15], v[20:23], v[16:19], v[0:15]
	v_or_b32_e32 v16, v96, v195
	v_lshlrev_b32_e32 v67, 7, v16
	v_or_b32_e32 v16, v67, v108
	ds_read_b128 v[16:19], v16
	s_waitcnt lgkmcnt(0)
	v_mfma_f32_32x32x16_bf16 v[16:31], v[16:19], v[60:63], 0
	v_or_b32_e32 v60, v67, v107
	ds_read_b128 v[60:63], v60
	s_waitcnt lgkmcnt(0)
	v_mfma_f32_32x32x16_bf16 v[16:31], v[60:63], v[52:55], v[16:31]
	v_or_b32_e32 v52, v67, v106
	ds_read_b128 v[52:55], v52
	s_waitcnt lgkmcnt(0)
	v_mfma_f32_32x32x16_bf16 v[16:31], v[52:55], v[56:59], v[16:31]
	v_or_b32_e32 v52, v67, v105
	ds_read_b128 v[52:55], v52
	s_waitcnt lgkmcnt(0)
	v_mfma_f32_32x32x16_bf16 v[16:31], v[52:55], v[48:51], v[16:31]
	v_add_u32_e32 v48, v103, v96
	v_sub_u32_e32 v49, v48, v101
	v_add_u32_e32 v50, 64, v49
	v_cmp_gt_u32_e32 vcc, s27, v50
	v_cmp_gt_u32_e64 s[42:43], s18, v48
	s_and_b64 vcc, s[42:43], vcc
	v_or_b32_e32 v50, 1, v48
	v_add_u32_e32 v51, 0x41, v49
	s_nop 3
	v_cndmask_b32_e32 v16, v183, v16, vcc
	v_cmp_gt_u32_e32 vcc, s27, v51
	v_cmp_gt_u32_e64 s[42:43], s18, v50
	s_and_b64 vcc, s[42:43], vcc
	v_or_b32_e32 v50, 2, v48
	v_add_u32_e32 v51, 0x42, v49
	v_cndmask_b32_e32 v17, v183, v17, vcc
	v_cmp_gt_u32_e32 vcc, s27, v51
	v_cmp_gt_u32_e64 s[42:43], s18, v50
	s_and_b64 vcc, s[42:43], vcc
	v_or_b32_e32 v50, 3, v48
	v_add_u32_e32 v51, 0x43, v49
	v_cndmask_b32_e32 v18, v183, v18, vcc
	v_cmp_gt_u32_e32 vcc, s27, v51
	v_cmp_gt_u32_e64 s[42:43], s18, v50
	s_and_b64 vcc, s[42:43], vcc
	v_or_b32_e32 v50, 8, v48
	v_add_u32_e32 v51, 0x48, v49
	v_cndmask_b32_e32 v19, v183, v19, vcc
	v_cmp_gt_u32_e32 vcc, s27, v51
	v_cmp_gt_u32_e64 s[42:43], s18, v50
	s_and_b64 vcc, s[42:43], vcc
	v_or_b32_e32 v50, 9, v48
	v_add_u32_e32 v51, 0x49, v49
	v_cndmask_b32_e32 v20, v183, v20, vcc
	v_cmp_gt_u32_e32 vcc, s27, v51
	v_cmp_gt_u32_e64 s[42:43], s18, v50
	s_and_b64 vcc, s[42:43], vcc
	v_or_b32_e32 v50, 10, v48
	v_add_u32_e32 v51, 0x4a, v49
	v_cndmask_b32_e32 v21, v183, v21, vcc
	v_cmp_gt_u32_e32 vcc, s27, v51
	v_cmp_gt_u32_e64 s[42:43], s18, v50
	s_and_b64 vcc, s[42:43], vcc
	v_or_b32_e32 v50, 11, v48
	v_add_u32_e32 v51, 0x4b, v49
	v_cndmask_b32_e32 v22, v183, v22, vcc
	v_cmp_gt_u32_e32 vcc, s27, v51
	v_cmp_gt_u32_e64 s[42:43], s18, v50
	s_and_b64 vcc, s[42:43], vcc
	v_or_b32_e32 v50, 16, v48
	v_add_u32_e32 v51, 0x50, v49
	v_cndmask_b32_e32 v23, v183, v23, vcc
	v_cmp_gt_u32_e32 vcc, s27, v51
	v_cmp_gt_u32_e64 s[42:43], s18, v50
	s_and_b64 vcc, s[42:43], vcc
	v_or_b32_e32 v50, 17, v48
	v_add_u32_e32 v51, 0x51, v49
	v_cndmask_b32_e32 v24, v183, v24, vcc
	v_cmp_gt_u32_e32 vcc, s27, v51
	v_cmp_gt_u32_e64 s[42:43], s18, v50
	s_and_b64 vcc, s[42:43], vcc
	v_or_b32_e32 v50, 18, v48
	v_add_u32_e32 v51, 0x52, v49
	v_cndmask_b32_e32 v25, v183, v25, vcc
	v_cmp_gt_u32_e32 vcc, s27, v51
	v_cmp_gt_u32_e64 s[42:43], s18, v50
	s_and_b64 vcc, s[42:43], vcc
	v_or_b32_e32 v50, 19, v48
	v_add_u32_e32 v51, 0x53, v49
	v_cndmask_b32_e32 v26, v183, v26, vcc
	v_cmp_gt_u32_e32 vcc, s27, v51
	v_cmp_gt_u32_e64 s[42:43], s18, v50
	s_and_b64 vcc, s[42:43], vcc
	v_or_b32_e32 v50, 24, v48
	v_add_u32_e32 v51, 0x58, v49
	v_cndmask_b32_e32 v27, v183, v27, vcc
	v_cmp_gt_u32_e32 vcc, s27, v51
	v_cmp_gt_u32_e64 s[42:43], s18, v50
	s_and_b64 vcc, s[42:43], vcc
	v_or_b32_e32 v50, 25, v48
	v_add_u32_e32 v51, 0x59, v49
	v_cndmask_b32_e32 v28, v183, v28, vcc
	v_cmp_gt_u32_e32 vcc, s27, v51
	v_cmp_gt_u32_e64 s[42:43], s18, v50
	s_and_b64 vcc, s[42:43], vcc
	v_or_b32_e32 v50, 26, v48
	v_add_u32_e32 v51, 0x5a, v49
	v_cndmask_b32_e32 v29, v183, v29, vcc
	v_cmp_gt_u32_e32 vcc, s27, v51
	v_cmp_gt_u32_e64 s[42:43], s18, v50
	s_and_b64 vcc, s[42:43], vcc
	v_or_b32_e32 v48, 27, v48
	v_add_u32_e32 v49, 0x5b, v49
	v_cndmask_b32_e32 v30, v183, v30, vcc
	v_cmp_gt_u32_e32 vcc, s27, v49
	v_cmp_gt_u32_e64 s[42:43], s18, v48
	v_max_f32_e32 v48, v17, v17
	v_max_f32_e32 v49, v16, v16
	v_max_f32_e32 v48, v49, v48
	v_max3_f32 v48, v48, v18, v19
	v_max3_f32 v48, v48, v20, v21
	v_max3_f32 v48, v48, v22, v23
	v_max3_f32 v48, v48, v24, v25
	s_and_b64 vcc, s[42:43], vcc
	v_max3_f32 v48, v48, v26, v27
	v_cndmask_b32_e32 v31, v183, v31, vcc
	v_max3_f32 v48, v48, v28, v29
	v_max3_f32 v48, v48, v30, v31
	ds_bpermute_b32 v49, v99, v48
	s_waitcnt lgkmcnt(0)
	v_max3_f32 v49, v65, v48, v49
	v_sub_f32_e32 v16, v16, v49
	v_exp_f32_e32 v79, v16
	v_sub_f32_e32 v16, v17, v49
	v_exp_f32_e32 v81, v16
	v_sub_f32_e32 v16, v18, v49
	v_exp_f32_e32 v83, v16
	v_sub_f32_e32 v16, v19, v49
	v_exp_f32_e32 v85, v16
	v_sub_f32_e32 v16, v20, v49
	v_exp_f32_e32 v87, v16
	v_sub_f32_e32 v16, v21, v49
	v_exp_f32_e32 v89, v16
	v_sub_f32_e32 v16, v22, v49
	v_sub_f32_e32 v48, v65, v49
	v_exp_f32_e32 v91, v16
	v_sub_f32_e32 v16, v23, v49
	v_exp_f32_e32 v93, v16
	v_sub_f32_e32 v16, v24, v49
	v_exp_f32_e32 v48, v48
	v_exp_f32_e32 v65, v16
	v_sub_f32_e32 v16, v25, v49
	v_exp_f32_e32 v67, v16
	v_sub_f32_e32 v16, v26, v49
	v_exp_f32_e32 v69, v16
	v_sub_f32_e32 v16, v27, v49
	v_exp_f32_e32 v71, v16
	v_sub_f32_e32 v16, v28, v49
	v_pk_mul_f32 v[22:23], v[38:39], v[48:49] op_sel_hi:[1,0]
	v_or_b32_e32 v38, v104, v96
	v_exp_f32_e32 v73, v16
	v_sub_f32_e32 v16, v29, v49
	v_pk_mul_f32 v[26:27], v[42:43], v[48:49] op_sel_hi:[1,0]
	v_lshlrev_b32_e32 v42, 6, v38
	v_exp_f32_e32 v75, v16
	v_sub_f32_e32 v16, v30, v49
	v_pk_mul_f32 v[24:25], v[40:41], v[48:49] op_sel_hi:[1,0]
	v_or3_b32 v40, v42, s24, v100
	v_or_b32_e32 v43, v42, v100
	v_exp_f32_e32 v77, v16
	v_sub_f32_e32 v16, v31, v49
	ds_read_b64_tr_b16 v[38:39], v43 offset:49152
	ds_read_b64_tr_b16 v[40:41], v40 offset:49152
	v_exp_f32_e32 v50, v16
	v_pk_mul_f32 v[16:17], v[32:33], v[48:49] op_sel_hi:[1,0]
	v_pk_add_f32 v[32:33], v[78:79], v[94:95]
	v_pk_mul_f32 v[30:31], v[46:47], v[48:49] op_sel_hi:[1,0]
	v_pk_add_f32 v[32:33], v[80:81], v[32:33]
	v_pk_mul_f32 v[28:29], v[44:45], v[48:49] op_sel_hi:[1,0]
	v_pk_add_f32 v[32:33], v[82:83], v[32:33]
	v_pk_mul_f32 v[20:21], v[36:37], v[48:49] op_sel_hi:[1,0]
	v_pk_mul_f32 v[18:19], v[34:35], v[48:49] op_sel_hi:[1,0]
	v_pk_add_f32 v[32:33], v[84:85], v[32:33]
	v_cvt_pk_bf16_f32 v34, v79, v81
	v_cvt_pk_bf16_f32 v35, v83, v85
	v_cvt_pk_bf16_f32 v36, v87, v89
	v_cvt_pk_bf16_f32 v37, v91, v93
	v_pk_add_f32 v[32:33], v[86:87], v[32:33]
	v_pk_mul_f32 v[14:15], v[14:15], v[48:49] op_sel_hi:[1,0]
	s_waitcnt lgkmcnt(0)
	v_mfma_f32_32x32x16_bf16 v[16:31], v[38:41], v[34:37], v[16:31]
	v_add_u32_e32 v38, 0x12000, v43
	v_add_u32_e32 v40, 0x12200, v43
	v_add_f32_e64 v32, v88, v32
	v_add_f32_e64 v33, v89, v33
	ds_read_b64_tr_b16 v[38:39], v38
	ds_read_b64_tr_b16 v[40:41], v40
	v_pk_add_f32 v[32:33], v[90:91], v[32:33]
	v_pk_mul_f32 v[12:13], v[12:13], v[48:49] op_sel_hi:[1,0]
	v_pk_add_f32 v[32:33], v[92:93], v[32:33]
	v_pk_mul_f32 v[10:11], v[10:11], v[48:49] op_sel_hi:[1,0]
	v_pk_add_f32 v[32:33], v[64:65], v[32:33]
	v_pk_mul_f32 v[8:9], v[8:9], v[48:49] op_sel_hi:[1,0]
	v_pk_mul_f32 v[6:7], v[6:7], v[48:49] op_sel_hi:[1,0]
	v_pk_mul_f32 v[4:5], v[4:5], v[48:49] op_sel_hi:[1,0]
	v_pk_mul_f32 v[2:3], v[2:3], v[48:49] op_sel_hi:[1,0]
	v_pk_mul_f32 v[0:1], v[0:1], v[48:49] op_sel_hi:[1,0]
	v_pk_add_f32 v[32:33], v[66:67], v[32:33]
	s_nop 0
	v_pk_add_f32 v[32:33], v[68:69], v[32:33]
	s_waitcnt lgkmcnt(0)
	v_mfma_f32_32x32x16_bf16 v[0:15], v[38:41], v[34:37], v[0:15]
	v_or3_b32 v38, v42, s19, v100
	v_or3_b32 v40, v42, s26, v100
	v_add_f32_e64 v32, v70, v32
	v_add_f32_e64 v33, v71, v33
	ds_read_b64_tr_b16 v[38:39], v38 offset:49152
	ds_read_b64_tr_b16 v[40:41], v40 offset:49152
	v_pk_add_f32 v[32:33], v[72:73], v[32:33]
	v_cvt_pk_bf16_f32 v34, v65, v67
	v_pk_add_f32 v[32:33], v[74:75], v[32:33]
	v_cvt_pk_bf16_f32 v35, v69, v71
	v_pk_add_f32 v[32:33], v[76:77], v[32:33]
	v_cvt_pk_bf16_f32 v36, v73, v75
	v_cvt_pk_bf16_f32 v37, v77, v50
	v_add_f32_e32 v33, v33, v50
	v_fmac_f32_e32 v33, v32, v48
	s_waitcnt lgkmcnt(0)
	v_mfma_f32_32x32x16_bf16 v[16:31], v[38:41], v[34:37], v[16:31]
	v_add_u32_e32 v38, 0x12400, v43
	v_add_u32_e32 v40, 0x12600, v43
	ds_read_b64_tr_b16 v[38:39], v38
	ds_read_b64_tr_b16 v[40:41], v40
	ds_bpermute_b32 v32, v99, v33
	s_waitcnt lgkmcnt(0)
	s_barrier
	v_mfma_f32_32x32x16_bf16 v[0:15], v[38:41], v[34:37], v[0:15]
	v_add_f32_e32 v34, v33, v32
	v_div_scale_f32 v32, s[18:19], v34, v34, 1.0
	v_rcp_f32_e32 v33, v32
	s_nop 0
	v_fma_f32 v35, -v32, v33, 1.0
	v_fmac_f32_e32 v33, v35, v33
	v_div_scale_f32 v35, vcc, 1.0, v34, 1.0
	v_mul_f32_e32 v36, v35, v33
	v_fma_f32 v37, -v32, v36, v35
	v_fmac_f32_e32 v36, v37, v33
	v_fma_f32 v32, -v32, v36, v35
	v_div_fmas_f32 v32, v32, v33, v36
	v_div_fixup_f32 v36, v32, v34, 1.0
	v_lshl_add_u32 v32, v194, 5, s16
	v_or_b32_e32 v32, v32, v195
	v_lshlrev_b32_e32 v32, s15, v32
	v_add_u32_e32 v32, s17, v32
	s_mov_b32 s15, s31
	v_ashrrev_i32_e32 v33, 31, v32
	v_lshl_add_u64 v[32:33], s[14:15], 0, v[32:33]
	v_readlane_b32 s14, v254, 58
	v_lshlrev_b64 v[38:39], 9, v[32:33]
	v_readlane_b32 s15, v254, 59
	v_pk_mul_f32 v[16:17], v[36:37], v[16:17] op_sel_hi:[0,1]
	v_pk_mul_f32 v[18:19], v[36:37], v[18:19] op_sel_hi:[0,1]
	v_lshl_add_u64 v[38:39], s[14:15], 0, v[38:39]
	v_lshl_add_u64 v[38:39], v[38:39], 0, s[30:31]
	v_pk_mul_f32 v[0:1], v[36:37], v[0:1] op_sel_hi:[0,1]
	v_pk_mul_f32 v[2:3], v[36:37], v[2:3] op_sel_hi:[0,1]
	v_lshl_add_u64 v[38:39], v[38:39], 0, v[168:169]
	v_cvt_pk_bf16_f32 v16, v16, v17
	v_cvt_pk_bf16_f32 v17, v18, v19
	v_cvt_pk_bf16_f32 v0, v0, v1
	v_cvt_pk_bf16_f32 v1, v2, v3
	global_store_dwordx2 v[38:39], v[16:17], off
	v_pk_mul_f32 v[16:17], v[36:37], v[20:21] op_sel_hi:[0,1]
	v_pk_mul_f32 v[18:19], v[36:37], v[22:23] op_sel_hi:[0,1]
	global_store_dwordx2 v[38:39], v[0:1], off offset:64
	v_pk_mul_f32 v[0:1], v[36:37], v[4:5] op_sel_hi:[0,1]
	v_pk_mul_f32 v[2:3], v[36:37], v[6:7] op_sel_hi:[0,1]
	v_cvt_pk_bf16_f32 v16, v16, v17
	v_cvt_pk_bf16_f32 v17, v18, v19
	v_cvt_pk_bf16_f32 v0, v0, v1
	v_cvt_pk_bf16_f32 v1, v2, v3
	global_store_dwordx2 v[38:39], v[16:17], off offset:16
	v_pk_mul_f32 v[16:17], v[36:37], v[24:25] op_sel_hi:[0,1]
	v_pk_mul_f32 v[18:19], v[36:37], v[26:27] op_sel_hi:[0,1]
	global_store_dwordx2 v[38:39], v[0:1], off offset:80
	v_pk_mul_f32 v[0:1], v[36:37], v[8:9] op_sel_hi:[0,1]
	v_pk_mul_f32 v[2:3], v[36:37], v[10:11] op_sel_hi:[0,1]
	v_cvt_pk_bf16_f32 v16, v16, v17
	v_cvt_pk_bf16_f32 v17, v18, v19
	v_cvt_pk_bf16_f32 v0, v0, v1
	v_cvt_pk_bf16_f32 v1, v2, v3
	global_store_dwordx2 v[38:39], v[16:17], off offset:32
	v_pk_mul_f32 v[16:17], v[36:37], v[28:29] op_sel_hi:[0,1]
	v_pk_mul_f32 v[18:19], v[36:37], v[30:31] op_sel_hi:[0,1]
	global_store_dwordx2 v[38:39], v[0:1], off offset:96
	v_pk_mul_f32 v[0:1], v[36:37], v[12:13] op_sel_hi:[0,1]
	v_pk_mul_f32 v[2:3], v[36:37], v[14:15] op_sel_hi:[0,1]
	v_cvt_pk_bf16_f32 v16, v16, v17
	v_cvt_pk_bf16_f32 v17, v18, v19
	v_cvt_pk_bf16_f32 v0, v0, v1
	v_cvt_pk_bf16_f32 v1, v2, v3
	v_cmp_gt_u32_e32 vcc, 32, v98
	global_store_dwordx2 v[38:39], v[16:17], off offset:48
	global_store_dwordx2 v[38:39], v[0:1], off offset:112
	s_and_saveexec_b64 s[14:15], vcc
	s_xor_b64 s[14:15], exec, s[14:15]
	s_cbranch_execz .LBB0_191
	v_log_f32_e32 v2, v34
	v_readlane_b32 s16, v254, 54
	v_readlane_b32 s17, v254, 55
	s_lshl_b32 s30, s5, 2
	v_add_f32_e32 v2, v49, v2
	v_lshl_add_u64 v[0:1], v[32:33], 4, s[16:17]
	v_lshl_add_u64 v[0:1], v[0:1], 0, s[30:31]
	global_store_dword v[0:1], v2, off

.LBB0_209:
	s_and_b32 s55, s24, 3
	v_and_b32_e32 v7, 15, v6
	v_and_b32_e32 v135, 48, v6
	v_lshlrev_b32_e32 v6, 2, v6
	v_lshl_add_u64 v[8:9], s[40:41], 0, v[168:169]
	v_mov_b32_e32 v129, v169
	v_lshl_or_b32 v134, s27, 6, v7
	v_lshl_or_b32 v7, v7, 6, v135
	v_and_b32_e32 v6, 32, v6
	s_lshl_b32 s24, s27, 13
	s_lshl_b32 s27, s55, 12
	s_add_i32 s56, s16, 0x18000
	v_lshl_add_u64 v[10:11], s[40:41], 0, v[128:129]
	v_bitop3_b32 v136, v7, s27, v6 bitop3:0xde
	v_bitop3_b32 v137, v7, s24, v6 bitop3:0xde
	v_lshl_add_u64 v[6:7], v[8:9], 0, s[34:35]
	s_mov_b32 m0, s56
	s_add_i32 s85, s16, 0x1a000
	v_lshl_add_u64 v[12:13], s[42:43], 0, v[168:169]
	s_and_b32 s57, s62, 7
	s_waitcnt vmcnt(2)
	s_barrier
	global_load_lds_dwordx4 v[6:7], off
	v_lshl_add_u64 v[6:7], v[10:11], 0, s[34:35]
	s_mov_b32 m0, s85
	s_add_i32 s86, s16, 0x8000
	s_add_i32 s87, s16, 0xa000
	v_lshl_add_u64 v[14:15], s[42:43], 0, v[128:129]
	global_load_lds_dwordx4 v[6:7], off
	v_lshl_add_u64 v[6:7], v[12:13], 0, s[34:35]
	s_mov_b32 m0, s86
	s_add_u32 s36, s40, 0x40080
	global_load_lds_dwordx4 v[6:7], off
	v_lshl_add_u64 v[6:7], v[14:15], 0, s[34:35]
	s_mov_b32 m0, s87
	s_addc_u32 s37, s41, 0
	s_add_i32 s90, s16, 0x1c000
	global_load_lds_dwordx4 v[6:7], off
	v_lshl_add_u64 v[6:7], s[36:37], 0, v[168:169]
	s_mov_b32 m0, s90
	s_add_i32 s24, s16, 0x1e000
	global_load_lds_dwordx4 v[6:7], off
	v_lshl_add_u64 v[6:7], s[36:37], 0, v[128:129]
	s_mov_b32 m0, s24
	s_add_i32 s26, s26, s57
	global_load_lds_dwordx4 v[6:7], off
	s_ashr_i32 s27, s26, 31
	s_lshl_b64 s[26:27], s[26:27], 19
	v_lshlrev_b32_e32 v6, 14, v0
	s_add_u32 s60, s74, s26
	v_and_b32_e32 v6, 0xffff8000, v6
	s_addc_u32 s91, s75, s27
	v_lshl_add_u32 v1, v1, 11, v6
	v_and_b32_e32 v0, 1, v0
	v_lshl_or_b32 v0, v0, 6, v1
	s_add_u32 s26, s18, s26
	v_lshl_add_u32 v0, v3, 1, v0
	v_mov_b32_e32 v1, v169
	s_addc_u32 s27, s19, s27
	v_lshl_add_u64 v[130:131], s[26:27], 0, v[0:1]
	v_lshlrev_b32_e32 v0, 14, v2
	v_and_b32_e32 v0, 0xffff8000, v0
	v_lshl_add_u32 v0, v4, 11, v0
	v_and_b32_e32 v1, 1, v2
	v_lshl_or_b32 v0, v1, 6, v0
	s_waitcnt vmcnt(6)
	v_lshl_add_u32 v0, v5, 1, v0
	v_mov_b32_e32 v1, v169
	v_lshl_add_u64 v[132:133], s[26:27], 0, v[0:1]
	s_add_u32 s92, s30, s14
	v_mov_b32_e32 v0, 0
	s_addc_u32 s93, s61, s15
	s_mov_b32 s94, -2
	s_mov_b64 s[44:45], 0
	v_mov_b32_e32 v1, v0
	v_mov_b32_e32 v2, v0
	v_mov_b32_e32 v3, v0
	v_mov_b32_e32 v4, v0
	v_mov_b32_e32 v5, v0
	v_mov_b32_e32 v6, v0
	v_mov_b32_e32 v7, v0
	v_mov_b32_e32 v8, v0
	v_mov_b32_e32 v9, v0
	v_mov_b32_e32 v10, v0
	v_mov_b32_e32 v11, v0
	v_mov_b32_e32 v12, v0
	v_mov_b32_e32 v13, v0
	v_mov_b32_e32 v14, v0
	v_mov_b32_e32 v15, v0
	v_mov_b32_e32 v16, v0
	v_mov_b32_e32 v17, v0
	v_mov_b32_e32 v18, v0
	v_mov_b32_e32 v19, v0
	v_mov_b32_e32 v20, v0
	v_mov_b32_e32 v21, v0
	v_mov_b32_e32 v22, v0
	v_mov_b32_e32 v23, v0
	v_mov_b32_e32 v24, v0
	v_mov_b32_e32 v25, v0
	v_mov_b32_e32 v26, v0
	v_mov_b32_e32 v27, v0
	v_mov_b32_e32 v28, v0
	v_mov_b32_e32 v29, v0
	v_mov_b32_e32 v30, v0
	v_mov_b32_e32 v31, v0
	v_mov_b32_e32 v32, v0
	v_mov_b32_e32 v33, v0
	v_mov_b32_e32 v34, v0
	v_mov_b32_e32 v35, v0
	v_mov_b32_e32 v36, v0
	v_mov_b32_e32 v37, v0
	v_mov_b32_e32 v38, v0
	v_mov_b32_e32 v39, v0
	v_mov_b32_e32 v40, v0
	v_mov_b32_e32 v41, v0
	v_mov_b32_e32 v42, v0
	v_mov_b32_e32 v43, v0
	v_mov_b32_e32 v44, v0
	v_mov_b32_e32 v45, v0
	v_mov_b32_e32 v46, v0
	v_mov_b32_e32 v47, v0
	v_mov_b32_e32 v48, v0
	v_mov_b32_e32 v49, v0
	v_mov_b32_e32 v50, v0
	v_mov_b32_e32 v51, v0
	v_mov_b32_e32 v52, v0
	v_mov_b32_e32 v53, v0
	v_mov_b32_e32 v54, v0
	v_mov_b32_e32 v55, v0
	v_mov_b32_e32 v56, v0
	v_mov_b32_e32 v57, v0
	v_mov_b32_e32 v58, v0
	v_mov_b32_e32 v59, v0
	v_mov_b32_e32 v60, v0
	v_mov_b32_e32 v61, v0
	v_mov_b32_e32 v62, v0
	v_mov_b32_e32 v63, v0
	v_mov_b32_e32 v64, v0
	v_mov_b32_e32 v65, v0
	v_mov_b32_e32 v66, v0
	v_mov_b32_e32 v67, v0
	v_mov_b32_e32 v68, v0
	v_mov_b32_e32 v69, v0
	v_mov_b32_e32 v70, v0
	v_mov_b32_e32 v71, v0
	v_mov_b32_e32 v72, v0
	v_mov_b32_e32 v73, v0
	v_mov_b32_e32 v74, v0
	v_mov_b32_e32 v75, v0
	v_mov_b32_e32 v76, v0
	v_mov_b32_e32 v77, v0
	v_mov_b32_e32 v78, v0
	v_mov_b32_e32 v79, v0
	v_mov_b32_e32 v80, v0
	v_mov_b32_e32 v81, v0
	v_mov_b32_e32 v82, v0
	v_mov_b32_e32 v83, v0
	v_mov_b32_e32 v84, v0
	v_mov_b32_e32 v85, v0
	v_mov_b32_e32 v86, v0
	v_mov_b32_e32 v87, v0
	v_mov_b32_e32 v88, v0
	v_mov_b32_e32 v89, v0
	v_mov_b32_e32 v90, v0
	v_mov_b32_e32 v91, v0
	v_mov_b32_e32 v92, v0
	v_mov_b32_e32 v93, v0
	v_mov_b32_e32 v94, v0
	v_mov_b32_e32 v95, v0
	v_mov_b32_e32 v96, v0
	v_mov_b32_e32 v97, v0
	v_mov_b32_e32 v98, v0
	v_mov_b32_e32 v99, v0
	v_mov_b32_e32 v100, v0
	v_mov_b32_e32 v101, v0
	v_mov_b32_e32 v102, v0
	v_mov_b32_e32 v103, v0
	v_mov_b32_e32 v104, v0
	v_mov_b32_e32 v105, v0
	v_mov_b32_e32 v106, v0
	v_mov_b32_e32 v107, v0
	v_mov_b32_e32 v108, v0
	v_mov_b32_e32 v109, v0
	v_mov_b32_e32 v110, v0
	v_mov_b32_e32 v111, v0
	v_mov_b32_e32 v112, v0
	v_mov_b32_e32 v113, v0
	v_mov_b32_e32 v114, v0
	v_mov_b32_e32 v115, v0
	v_mov_b32_e32 v116, v0
	v_mov_b32_e32 v117, v0
	v_mov_b32_e32 v118, v0
	v_mov_b32_e32 v119, v0
	v_mov_b32_e32 v120, v0
	v_mov_b32_e32 v121, v0
	v_mov_b32_e32 v122, v0
	v_mov_b32_e32 v123, v0
	v_mov_b32_e32 v124, v0
	v_mov_b32_e32 v125, v0
	v_mov_b32_e32 v126, v0
	v_mov_b32_e32 v127, v0
	s_nop 0
	s_nop 0
	s_nop 0
	s_nop 0
	s_nop 0
	s_nop 0
	s_nop 0
	s_nop 0
	s_nop 0
	s_nop 0
	s_nop 0
	s_nop 0
	s_nop 0
	s_nop 0
	s_nop 0
	s_barrier
